# grid barrier spin loops without s_sleep
# baseline (speedup 1.0000x reference)
; __global__ void __launch_bounds__(NTHR) fwd_megakernel(Params p) {
;     ...
;     if (p.ws == nullptr) grid.sync();
.LBB0_105:
	s_nop 0
	global_load_dword v2, v0, s[2:3] offset:32 sc1
	s_waitcnt vmcnt(0)
	v_and_b32_e32 v2, 0xffff0000, v2
	v_cmp_ne_u32_e32 vcc, v2, v1
	s_or_b64 s[4:5], vcc, s[4:5]
	s_andn2_b64 exec, exec, s[4:5]
	s_cbranch_execnz .LBB0_105

; DI unsigned xb_ld(unsigned* p)              { return __hip_atomic_load(p, __ATOMIC_RELAXED, __HIP_MEMORY_SCOPE_AGENT); }
; DI void xcd_barrier_complete(unsigned* bar, unsigned x, unsigned& nloc, unsigned& nx) {
;     ...
;     for (;;) {
;         sum = 0u; cnt = 0u; mine = 0u;
; #pragma unroll
;         for (unsigned j = 0; j < 16; ++j) { const unsigned c = xb_ld(&bar[XB_XCNT(j)]); sum += c; cnt += (c > 0u) ? 1u : 0u; mine = (j == x) ? c : mine; }
;         if (sum == G) break;
;         __builtin_amdgcn_s_sleep(1);
;         if ((++sp & 255u) == 0u) { if (xb_ld(&bar[XB_TMO])) break; if (sp > XB_SPIN_CAP) { atomicAdd(&bar[XB_TMO], 1u); break; } }
;     }
.LBB0_112:
	global_load_dword v15, v16, s[4:5] sc1
	s_waitcnt lgkmcnt(0)
	global_load_dword v0, v16, s[6:7] sc1
	global_load_dword v1, v16, s[8:9] sc1
	global_load_dword v2, v16, s[10:11] sc1
	global_load_dword v3, v16, s[12:13] sc1
	global_load_dword v4, v16, s[14:15] sc1
	global_load_dword v5, v16, s[20:21] sc1
	global_load_dword v6, v16, s[28:29] sc1
	global_load_dword v7, v16, s[30:31] sc1
	global_load_dword v8, v16, s[34:35] sc1
	global_load_dword v9, v16, s[36:37] sc1
	global_load_dword v10, v16, s[38:39] sc1
	global_load_dword v11, v16, s[40:41] sc1
	global_load_dword v12, v16, s[42:43] sc1
	global_load_dword v13, v16, s[44:45] sc1
	global_load_dword v14, v16, s[46:47] sc1
	s_mov_b64 s[50:51], -1
	s_mov_b64 s[56:57], -1
	s_waitcnt vmcnt(14)
	v_add_u32_e32 v17, v0, v15
	s_waitcnt vmcnt(13)
	v_add_u32_e32 v17, v17, v1
	s_waitcnt vmcnt(12)
	v_add_u32_e32 v17, v17, v2
	s_waitcnt vmcnt(11)
	v_add_u32_e32 v17, v17, v3
	s_waitcnt vmcnt(10)
	v_add_u32_e32 v17, v17, v4
	s_waitcnt vmcnt(9)
	v_add_u32_e32 v17, v17, v5
	s_waitcnt vmcnt(8)
	v_add_u32_e32 v17, v17, v6
	s_waitcnt vmcnt(7)
	v_add_u32_e32 v17, v17, v7
	s_waitcnt vmcnt(6)
	v_add_u32_e32 v17, v17, v8
	s_waitcnt vmcnt(5)
	v_add_u32_e32 v17, v17, v9
	s_waitcnt vmcnt(4)
	v_add_u32_e32 v17, v17, v10
	s_waitcnt vmcnt(3)
	v_add_u32_e32 v17, v17, v11
	s_waitcnt vmcnt(2)
	v_add_u32_e32 v17, v17, v12
	s_waitcnt vmcnt(1)
	v_add_u32_e32 v17, v17, v13
	s_waitcnt vmcnt(0)
	v_add_u32_e32 v17, v17, v14
	v_cmp_eq_u32_e32 vcc, s26, v17
	s_cbranch_vccnz .LBB0_111
	s_and_b32 s50, s74, 0xff
	s_cmp_eq_u32 s50, 0
	s_mov_b64 s[50:51], -1
	s_mov_b64 s[72:73], -1
	s_nop 0
	s_cbranch_scc0 .LBB0_116
	global_load_dword v17, v16, s[2:3] sc1
	s_waitcnt vmcnt(0)
	v_cmp_eq_u32_e32 vcc, 0, v17
	s_cbranch_vccnz .LBB0_118
	s_mov_b64 s[72:73], 0

; DI unsigned xb_ld(unsigned* p)              { return __hip_atomic_load(p, __ATOMIC_RELAXED, __HIP_MEMORY_SCOPE_AGENT); }
; DI unsigned xb_add(unsigned* p, unsigned v) { return __hip_atomic_fetch_add(p, v, __ATOMIC_RELAXED, __HIP_MEMORY_SCOPE_AGENT); }
; #define XB_SPIN(cond, bar) do { unsigned _sp = 0; while (cond) { __builtin_amdgcn_s_sleep(1); \
;     if ((++_sp & 255u) == 0u) { if (xb_ld(&(bar)[XB_TMO])) break; if (_sp > XB_SPIN_CAP) { atomicAdd(&(bar)[XB_TMO], 1u); break; } } } } while (0)
; DI void xcd_barrier(const XcdBarrier& b) {
;     ...
;             else XB_SPIN(xb_ld(&bar[XB_TOPGEN]) == tg, bar);
;             __builtin_amdgcn_fence(__ATOMIC_ACQUIRE, "agent");
;             xb_add(&bar[XB_XGEN(b.x)], 1u);
;             asm volatile("s_waitcnt vmcnt(0)" ::: "memory");
;         } else {
;             XB_SPIN(xb_ld(&bar[XB_XGEN(b.x)]) == gen, bar);
.LBB0_130:
	s_and_b32 s28, s26, 0xff
	s_mov_b64 s[20:21], -1
	s_cmp_lg_u32 s28, 0
	s_mov_b64 s[30:31], -1
	s_nop 0
	s_cbranch_scc1 .LBB0_133
	global_load_dword v2, v0, s[8:9] sc1
	s_waitcnt vmcnt(0)
	v_cmp_eq_u32_e32 vcc, 0, v2
	s_cbranch_vccnz .LBB0_135
	s_mov_b64 s[30:31], 0
	s_mov_b64 s[28:29], -1

; DI unsigned xb_ld(unsigned* p)              { return __hip_atomic_load(p, __ATOMIC_RELAXED, __HIP_MEMORY_SCOPE_AGENT); }
; DI unsigned xb_add(unsigned* p, unsigned v) { return __hip_atomic_fetch_add(p, v, __ATOMIC_RELAXED, __HIP_MEMORY_SCOPE_AGENT); }
; #define XB_SPIN(cond, bar) do { unsigned _sp = 0; while (cond) { __builtin_amdgcn_s_sleep(1); \
;     if ((++_sp & 255u) == 0u) { if (xb_ld(&(bar)[XB_TMO])) break; if (_sp > XB_SPIN_CAP) { atomicAdd(&(bar)[XB_TMO], 1u); break; } } } } while (0)
; DI void xcd_barrier(const XcdBarrier& b) {
;     ...
;             else XB_SPIN(xb_ld(&bar[XB_TOPGEN]) == tg, bar);
;             __builtin_amdgcn_fence(__ATOMIC_ACQUIRE, "agent");
;             xb_add(&bar[XB_XGEN(b.x)], 1u);
;             asm volatile("s_waitcnt vmcnt(0)" ::: "memory");
;         } else {
;             XB_SPIN(xb_ld(&bar[XB_XGEN(b.x)]) == gen, bar);
.LBB0_147:
	s_and_b32 s20, s26, 0xff
	s_cmp_lg_u32 s20, 0
	s_mov_b64 s[28:29], -1
	s_nop 0
	s_cbranch_scc1 .LBB0_150
	global_load_dword v1, v0, s[8:9] sc1
	s_waitcnt vmcnt(0)
	v_cmp_eq_u32_e32 vcc, 0, v1
	s_cbranch_vccnz .LBB0_152
	s_mov_b64 s[28:29], 0
	s_mov_b64 s[20:21], -1

; DI unsigned xb_ld(unsigned* p)              { return __hip_atomic_load(p, __ATOMIC_RELAXED, __HIP_MEMORY_SCOPE_AGENT); }
; DI void xcd_barrier_complete(unsigned* bar, unsigned x, unsigned& nloc, unsigned& nx) {
;     ...
;     for (;;) {
;         sum = 0u; cnt = 0u; mine = 0u;
; #pragma unroll
;         for (unsigned j = 0; j < 16; ++j) { const unsigned c = xb_ld(&bar[XB_XCNT(j)]); sum += c; cnt += (c > 0u) ? 1u : 0u; mine = (j == x) ? c : mine; }
;         if (sum == G) break;
;         __builtin_amdgcn_s_sleep(1);
;         if ((++sp & 255u) == 0u) { if (xb_ld(&bar[XB_TMO])) break; if (sp > XB_SPIN_CAP) { atomicAdd(&bar[XB_TMO], 1u); break; } }
;     }
.LBB0_167:
	global_load_dword v15, v16, s[4:5] sc1
	s_waitcnt lgkmcnt(0)
	global_load_dword v0, v16, s[6:7] sc1
	global_load_dword v1, v16, s[8:9] sc1
	global_load_dword v2, v16, s[10:11] sc1
	global_load_dword v3, v16, s[12:13] sc1
	global_load_dword v4, v16, s[14:15] sc1
	global_load_dword v5, v16, s[20:21] sc1
	global_load_dword v6, v16, s[28:29] sc1
	global_load_dword v7, v16, s[30:31] sc1
	global_load_dword v8, v16, s[34:35] sc1
	global_load_dword v9, v16, s[36:37] sc1
	global_load_dword v10, v16, s[38:39] sc1
	global_load_dword v11, v16, s[40:41] sc1
	global_load_dword v12, v16, s[42:43] sc1
	global_load_dword v13, v16, s[44:45] sc1
	global_load_dword v14, v16, s[46:47] sc1
	s_mov_b64 s[50:51], -1
	s_mov_b64 s[54:55], -1
	s_waitcnt vmcnt(14)
	v_add_u32_e32 v17, v0, v15
	s_waitcnt vmcnt(13)
	v_add_u32_e32 v17, v17, v1
	s_waitcnt vmcnt(12)
	v_add_u32_e32 v17, v17, v2
	s_waitcnt vmcnt(11)
	v_add_u32_e32 v17, v17, v3
	s_waitcnt vmcnt(10)
	v_add_u32_e32 v17, v17, v4
	s_waitcnt vmcnt(9)
	v_add_u32_e32 v17, v17, v5
	s_waitcnt vmcnt(8)
	v_add_u32_e32 v17, v17, v6
	s_waitcnt vmcnt(7)
	v_add_u32_e32 v17, v17, v7
	s_waitcnt vmcnt(6)
	v_add_u32_e32 v17, v17, v8
	s_waitcnt vmcnt(5)
	v_add_u32_e32 v17, v17, v9
	s_waitcnt vmcnt(4)
	v_add_u32_e32 v17, v17, v10
	s_waitcnt vmcnt(3)
	v_add_u32_e32 v17, v17, v11
	s_waitcnt vmcnt(2)
	v_add_u32_e32 v17, v17, v12
	s_waitcnt vmcnt(1)
	v_add_u32_e32 v17, v17, v13
	s_waitcnt vmcnt(0)
	v_add_u32_e32 v17, v17, v14
	v_cmp_eq_u32_e32 vcc, s26, v17
	s_cbranch_vccnz .LBB0_166
	s_and_b32 s50, s58, 0xff
	s_cmp_eq_u32 s50, 0
	s_mov_b64 s[50:51], -1
	s_mov_b64 s[56:57], -1
	s_nop 0
	s_cbranch_scc0 .LBB0_171
	global_load_dword v17, v16, s[2:3] sc1
	s_waitcnt vmcnt(0)
	v_cmp_eq_u32_e32 vcc, 0, v17
	s_cbranch_vccnz .LBB0_173
	s_mov_b64 s[56:57], 0

; DI unsigned xb_ld(unsigned* p)              { return __hip_atomic_load(p, __ATOMIC_RELAXED, __HIP_MEMORY_SCOPE_AGENT); }
; DI void xcd_barrier_complete(unsigned* bar, unsigned x, unsigned& nloc, unsigned& nx) {
;     ...
;     for (;;) {
;         sum = 0u; cnt = 0u; mine = 0u;
; #pragma unroll
;         for (unsigned j = 0; j < 16; ++j) { const unsigned c = xb_ld(&bar[XB_XCNT(j)]); sum += c; cnt += (c > 0u) ? 1u : 0u; mine = (j == x) ? c : mine; }
;         if (sum == G) break;
;         __builtin_amdgcn_s_sleep(1);
;         if ((++sp & 255u) == 0u) { if (xb_ld(&bar[XB_TMO])) break; if (sp > XB_SPIN_CAP) { atomicAdd(&bar[XB_TMO], 1u); break; } }
;     }
.LBB0_276:
	global_load_dword v15, v16, s[4:5] sc1
	global_load_dword v0, v16, s[6:7] sc1
	global_load_dword v1, v16, s[8:9] sc1
	global_load_dword v2, v16, s[10:11] sc1
	global_load_dword v3, v16, s[12:13] sc1
	global_load_dword v4, v16, s[14:15] sc1
	global_load_dword v5, v16, s[28:29] sc1
	global_load_dword v6, v16, s[30:31] sc1
	global_load_dword v7, v16, s[34:35] sc1
	global_load_dword v8, v16, s[36:37] sc1
	global_load_dword v9, v16, s[38:39] sc1
	global_load_dword v10, v16, s[40:41] sc1
	global_load_dword v11, v16, s[42:43] sc1
	global_load_dword v12, v16, s[44:45] sc1
	global_load_dword v13, v16, s[46:47] sc1
	global_load_dword v14, v16, s[50:51] sc1
	s_mov_b64 s[54:55], -1
	s_mov_b64 s[56:57], -1
	s_waitcnt vmcnt(14)
	v_add_u32_e32 v17, v0, v15
	s_waitcnt vmcnt(13)
	v_add_u32_e32 v17, v17, v1
	s_waitcnt vmcnt(12)
	v_add_u32_e32 v17, v17, v2
	s_waitcnt vmcnt(11)
	v_add_u32_e32 v17, v17, v3
	s_waitcnt vmcnt(10)
	v_add_u32_e32 v17, v17, v4
	s_waitcnt vmcnt(9)
	v_add_u32_e32 v17, v17, v5
	s_waitcnt vmcnt(8)
	v_add_u32_e32 v17, v17, v6
	s_waitcnt vmcnt(7)
	v_add_u32_e32 v17, v17, v7
	s_waitcnt vmcnt(6)
	v_add_u32_e32 v17, v17, v8
	s_waitcnt vmcnt(5)
	v_add_u32_e32 v17, v17, v9
	s_waitcnt vmcnt(4)
	v_add_u32_e32 v17, v17, v10
	s_waitcnt vmcnt(3)
	v_add_u32_e32 v17, v17, v11
	s_waitcnt vmcnt(2)
	v_add_u32_e32 v17, v17, v12
	s_waitcnt vmcnt(1)
	v_add_u32_e32 v17, v17, v13
	s_waitcnt vmcnt(0)
	v_add_u32_e32 v17, v17, v14
	v_cmp_eq_u32_e32 vcc, s73, v17
	s_cbranch_vccnz .LBB0_275
	s_and_b32 s54, s72, 0xff
	s_cmp_eq_u32 s54, 0
	s_mov_b64 s[54:55], -1
	s_mov_b64 s[58:59], -1
	s_nop 0
	s_cbranch_scc0 .LBB0_280
	global_load_dword v17, v16, s[2:3] sc1
	s_waitcnt vmcnt(0)
	v_cmp_eq_u32_e32 vcc, 0, v17
	s_cbranch_vccnz .LBB0_282
	s_mov_b64 s[58:59], 0

; DI unsigned xb_ld(unsigned* p)              { return __hip_atomic_load(p, __ATOMIC_RELAXED, __HIP_MEMORY_SCOPE_AGENT); }
; DI unsigned xb_add(unsigned* p, unsigned v) { return __hip_atomic_fetch_add(p, v, __ATOMIC_RELAXED, __HIP_MEMORY_SCOPE_AGENT); }
; #define XB_SPIN(cond, bar) do { unsigned _sp = 0; while (cond) { __builtin_amdgcn_s_sleep(1); \
;     if ((++_sp & 255u) == 0u) { if (xb_ld(&(bar)[XB_TMO])) break; if (_sp > XB_SPIN_CAP) { atomicAdd(&(bar)[XB_TMO], 1u); break; } } } } while (0)
; DI void xcd_barrier(const XcdBarrier& b) {
;     ...
;             else XB_SPIN(xb_ld(&bar[XB_TOPGEN]) == tg, bar);
;             __builtin_amdgcn_fence(__ATOMIC_ACQUIRE, "agent");
;             xb_add(&bar[XB_XGEN(b.x)], 1u);
;             asm volatile("s_waitcnt vmcnt(0)" ::: "memory");
;         } else {
;             XB_SPIN(xb_ld(&bar[XB_XGEN(b.x)]) == gen, bar);
.LBB0_294:
	s_and_b32 s30, s36, 0xff
	s_mov_b64 s[28:29], -1
	s_cmp_lg_u32 s30, 0
	s_mov_b64 s[34:35], -1
	s_nop 0
	s_cbranch_scc1 .LBB0_297
	global_load_dword v2, v0, s[8:9] sc1
	s_waitcnt vmcnt(0)
	v_cmp_eq_u32_e32 vcc, 0, v2
	s_cbranch_vccnz .LBB0_299
	s_mov_b64 s[34:35], 0
	s_mov_b64 s[30:31], -1

; DI unsigned xb_ld(unsigned* p)              { return __hip_atomic_load(p, __ATOMIC_RELAXED, __HIP_MEMORY_SCOPE_AGENT); }
; DI unsigned xb_add(unsigned* p, unsigned v) { return __hip_atomic_fetch_add(p, v, __ATOMIC_RELAXED, __HIP_MEMORY_SCOPE_AGENT); }
; #define XB_SPIN(cond, bar) do { unsigned _sp = 0; while (cond) { __builtin_amdgcn_s_sleep(1); \
;     if ((++_sp & 255u) == 0u) { if (xb_ld(&(bar)[XB_TMO])) break; if (_sp > XB_SPIN_CAP) { atomicAdd(&(bar)[XB_TMO], 1u); break; } } } } while (0)
; DI void xcd_barrier(const XcdBarrier& b) {
;     ...
;             else XB_SPIN(xb_ld(&bar[XB_TOPGEN]) == tg, bar);
;             __builtin_amdgcn_fence(__ATOMIC_ACQUIRE, "agent");
;             xb_add(&bar[XB_XGEN(b.x)], 1u);
;             asm volatile("s_waitcnt vmcnt(0)" ::: "memory");
;         } else {
;             XB_SPIN(xb_ld(&bar[XB_XGEN(b.x)]) == gen, bar);
.LBB0_311:
	s_and_b32 s28, s36, 0xff
	s_cmp_lg_u32 s28, 0
	s_mov_b64 s[30:31], -1
	s_nop 0
	s_cbranch_scc1 .LBB0_314
	global_load_dword v1, v0, s[8:9] sc1
	s_waitcnt vmcnt(0)
	v_cmp_eq_u32_e32 vcc, 0, v1
	s_cbranch_vccnz .LBB0_316
	s_mov_b64 s[30:31], 0
	s_mov_b64 s[28:29], -1

; DI unsigned xb_ld(unsigned* p)              { return __hip_atomic_load(p, __ATOMIC_RELAXED, __HIP_MEMORY_SCOPE_AGENT); }
; DI void xcd_barrier_complete(unsigned* bar, unsigned x, unsigned& nloc, unsigned& nx) {
;     ...
;     for (;;) {
;         sum = 0u; cnt = 0u; mine = 0u;
; #pragma unroll
;         for (unsigned j = 0; j < 16; ++j) { const unsigned c = xb_ld(&bar[XB_XCNT(j)]); sum += c; cnt += (c > 0u) ? 1u : 0u; mine = (j == x) ? c : mine; }
;         if (sum == G) break;
;         __builtin_amdgcn_s_sleep(1);
;         if ((++sp & 255u) == 0u) { if (xb_ld(&bar[XB_TMO])) break; if (sp > XB_SPIN_CAP) { atomicAdd(&bar[XB_TMO], 1u); break; } }
;     }
.LBB0_374:
	global_load_dword v15, v16, s[8:9] sc1
	global_load_dword v0, v16, s[10:11] sc1
	global_load_dword v1, v16, s[12:13] sc1
	global_load_dword v2, v16, s[14:15] sc1
	global_load_dword v3, v16, s[28:29] sc1
	global_load_dword v4, v16, s[30:31] sc1
	global_load_dword v5, v16, s[34:35] sc1
	global_load_dword v6, v16, s[36:37] sc1
	global_load_dword v7, v16, s[38:39] sc1
	global_load_dword v8, v16, s[40:41] sc1
	global_load_dword v9, v16, s[42:43] sc1
	global_load_dword v10, v16, s[44:45] sc1
	global_load_dword v11, v16, s[46:47] sc1
	global_load_dword v12, v16, s[50:51] sc1
	global_load_dword v13, v16, s[54:55] sc1
	global_load_dword v14, v16, s[56:57] sc1
	s_mov_b64 s[58:59], -1
	s_mov_b64 s[72:73], -1
	s_waitcnt vmcnt(14)
	v_add_u32_e32 v17, v0, v15
	s_waitcnt vmcnt(13)
	v_add_u32_e32 v17, v17, v1
	s_waitcnt vmcnt(12)
	v_add_u32_e32 v17, v17, v2
	s_waitcnt vmcnt(11)
	v_add_u32_e32 v17, v17, v3
	s_waitcnt vmcnt(10)
	v_add_u32_e32 v17, v17, v4
	s_waitcnt vmcnt(9)
	v_add_u32_e32 v17, v17, v5
	s_waitcnt vmcnt(8)
	v_add_u32_e32 v17, v17, v6
	s_waitcnt vmcnt(7)
	v_add_u32_e32 v17, v17, v7
	s_waitcnt vmcnt(6)
	v_add_u32_e32 v17, v17, v8
	s_waitcnt vmcnt(5)
	v_add_u32_e32 v17, v17, v9
	s_waitcnt vmcnt(4)
	v_add_u32_e32 v17, v17, v10
	s_waitcnt vmcnt(3)
	v_add_u32_e32 v17, v17, v11
	s_waitcnt vmcnt(2)
	v_add_u32_e32 v17, v17, v12
	s_waitcnt vmcnt(1)
	v_add_u32_e32 v17, v17, v13
	s_waitcnt vmcnt(0)
	v_add_u32_e32 v17, v17, v14
	v_cmp_eq_u32_e32 vcc, s78, v17
	s_cbranch_vccnz .LBB0_373
	s_and_b32 s58, s76, 0xff
	s_cmp_eq_u32 s58, 0
	s_mov_b64 s[58:59], -1
	s_mov_b64 s[74:75], -1
	s_nop 0
	s_cbranch_scc0 .LBB0_378
	global_load_dword v17, v16, s[2:3] sc1
	s_waitcnt vmcnt(0)
	v_cmp_eq_u32_e32 vcc, 0, v17
	s_cbranch_vccnz .LBB0_380
	s_mov_b64 s[74:75], 0

; DI unsigned xb_ld(unsigned* p)              { return __hip_atomic_load(p, __ATOMIC_RELAXED, __HIP_MEMORY_SCOPE_AGENT); }
; DI unsigned xb_add(unsigned* p, unsigned v) { return __hip_atomic_fetch_add(p, v, __ATOMIC_RELAXED, __HIP_MEMORY_SCOPE_AGENT); }
; #define XB_SPIN(cond, bar) do { unsigned _sp = 0; while (cond) { __builtin_amdgcn_s_sleep(1); \
;     if ((++_sp & 255u) == 0u) { if (xb_ld(&(bar)[XB_TMO])) break; if (_sp > XB_SPIN_CAP) { atomicAdd(&(bar)[XB_TMO], 1u); break; } } } } while (0)
; DI void xcd_barrier(const XcdBarrier& b) {
;     ...
;             else XB_SPIN(xb_ld(&bar[XB_TOPGEN]) == tg, bar);
;             __builtin_amdgcn_fence(__ATOMIC_ACQUIRE, "agent");
;             xb_add(&bar[XB_XGEN(b.x)], 1u);
;             asm volatile("s_waitcnt vmcnt(0)" ::: "memory");
;         } else {
;             XB_SPIN(xb_ld(&bar[XB_XGEN(b.x)]) == gen, bar);
.LBB0_392:
	s_and_b32 s36, s40, 0xff
	s_mov_b64 s[34:35], -1
	s_cmp_lg_u32 s36, 0
	s_mov_b64 s[38:39], -1
	s_nop 0
	s_cbranch_scc1 .LBB0_395
	global_load_dword v2, v0, s[12:13] sc1
	s_waitcnt vmcnt(0)
	v_cmp_eq_u32_e32 vcc, 0, v2
	s_cbranch_vccnz .LBB0_397
	s_mov_b64 s[38:39], 0
	s_mov_b64 s[36:37], -1

; DI unsigned xb_ld(unsigned* p)              { return __hip_atomic_load(p, __ATOMIC_RELAXED, __HIP_MEMORY_SCOPE_AGENT); }
; DI unsigned xb_add(unsigned* p, unsigned v) { return __hip_atomic_fetch_add(p, v, __ATOMIC_RELAXED, __HIP_MEMORY_SCOPE_AGENT); }
; #define XB_SPIN(cond, bar) do { unsigned _sp = 0; while (cond) { __builtin_amdgcn_s_sleep(1); \
;     if ((++_sp & 255u) == 0u) { if (xb_ld(&(bar)[XB_TMO])) break; if (_sp > XB_SPIN_CAP) { atomicAdd(&(bar)[XB_TMO], 1u); break; } } } } while (0)
; DI void xcd_barrier(const XcdBarrier& b) {
;     ...
;             else XB_SPIN(xb_ld(&bar[XB_TOPGEN]) == tg, bar);
;             __builtin_amdgcn_fence(__ATOMIC_ACQUIRE, "agent");
;             xb_add(&bar[XB_XGEN(b.x)], 1u);
;             asm volatile("s_waitcnt vmcnt(0)" ::: "memory");
;         } else {
;             XB_SPIN(xb_ld(&bar[XB_XGEN(b.x)]) == gen, bar);
.LBB0_409:
	s_and_b32 s34, s40, 0xff
	s_cmp_lg_u32 s34, 0
	s_mov_b64 s[36:37], -1
	s_nop 0
	s_cbranch_scc1 .LBB0_412
	global_load_dword v1, v0, s[12:13] sc1
	s_waitcnt vmcnt(0)
	v_cmp_eq_u32_e32 vcc, 0, v1
	s_cbranch_vccnz .LBB0_414
	s_mov_b64 s[36:37], 0
	s_mov_b64 s[34:35], -1

; DI unsigned xb_ld(unsigned* p)              { return __hip_atomic_load(p, __ATOMIC_RELAXED, __HIP_MEMORY_SCOPE_AGENT); }
; DI void xcd_barrier_complete(unsigned* bar, unsigned x, unsigned& nloc, unsigned& nx) {
;     ...
;     for (;;) {
;         sum = 0u; cnt = 0u; mine = 0u;
; #pragma unroll
;         for (unsigned j = 0; j < 16; ++j) { const unsigned c = xb_ld(&bar[XB_XCNT(j)]); sum += c; cnt += (c > 0u) ? 1u : 0u; mine = (j == x) ? c : mine; }
;         if (sum == G) break;
;         __builtin_amdgcn_s_sleep(1);
;         if ((++sp & 255u) == 0u) { if (xb_ld(&bar[XB_TMO])) break; if (sp > XB_SPIN_CAP) { atomicAdd(&bar[XB_TMO], 1u); break; } }
;     }
.LBB0_456:
	global_load_dword v15, v16, s[6:7] sc1
	global_load_dword v0, v16, s[8:9] sc1
	global_load_dword v1, v16, s[10:11] sc1
	global_load_dword v2, v16, s[12:13] sc1
	global_load_dword v3, v16, s[14:15] sc1
	global_load_dword v4, v16, s[28:29] sc1
	global_load_dword v5, v16, s[30:31] sc1
	global_load_dword v6, v16, s[34:35] sc1
	global_load_dword v7, v16, s[36:37] sc1
	global_load_dword v8, v16, s[38:39] sc1
	global_load_dword v9, v16, s[40:41] sc1
	global_load_dword v10, v16, s[42:43] sc1
	global_load_dword v11, v16, s[44:45] sc1
	global_load_dword v12, v16, s[46:47] sc1
	global_load_dword v13, v16, s[50:51] sc1
	global_load_dword v14, v16, s[54:55] sc1
	s_mov_b64 s[56:57], -1
	s_mov_b64 s[58:59], -1
	s_waitcnt vmcnt(14)
	v_add_u32_e32 v17, v0, v15
	s_waitcnt vmcnt(13)
	v_add_u32_e32 v17, v17, v1
	s_waitcnt vmcnt(12)
	v_add_u32_e32 v17, v17, v2
	s_waitcnt vmcnt(11)
	v_add_u32_e32 v17, v17, v3
	s_waitcnt vmcnt(10)
	v_add_u32_e32 v17, v17, v4
	s_waitcnt vmcnt(9)
	v_add_u32_e32 v17, v17, v5
	s_waitcnt vmcnt(8)
	v_add_u32_e32 v17, v17, v6
	s_waitcnt vmcnt(7)
	v_add_u32_e32 v17, v17, v7
	s_waitcnt vmcnt(6)
	v_add_u32_e32 v17, v17, v8
	s_waitcnt vmcnt(5)
	v_add_u32_e32 v17, v17, v9
	s_waitcnt vmcnt(4)
	v_add_u32_e32 v17, v17, v10
	s_waitcnt vmcnt(3)
	v_add_u32_e32 v17, v17, v11
	s_waitcnt vmcnt(2)
	v_add_u32_e32 v17, v17, v12
	s_waitcnt vmcnt(1)
	v_add_u32_e32 v17, v17, v13
	s_waitcnt vmcnt(0)
	v_add_u32_e32 v17, v17, v14
	v_cmp_eq_u32_e32 vcc, s75, v17
	s_cbranch_vccnz .LBB0_455
	s_and_b32 s56, s74, 0xff
	s_cmp_eq_u32 s56, 0
	s_mov_b64 s[56:57], -1
	s_mov_b64 s[72:73], -1
	s_nop 0
	s_cbranch_scc0 .LBB0_460
	global_load_dword v17, v16, s[4:5] sc1
	s_waitcnt vmcnt(0)
	v_cmp_eq_u32_e32 vcc, 0, v17
	s_cbranch_vccnz .LBB0_462
	s_mov_b64 s[72:73], 0

; DI unsigned xb_ld(unsigned* p)              { return __hip_atomic_load(p, __ATOMIC_RELAXED, __HIP_MEMORY_SCOPE_AGENT); }
; DI unsigned xb_add(unsigned* p, unsigned v) { return __hip_atomic_fetch_add(p, v, __ATOMIC_RELAXED, __HIP_MEMORY_SCOPE_AGENT); }
; #define XB_SPIN(cond, bar) do { unsigned _sp = 0; while (cond) { __builtin_amdgcn_s_sleep(1); \
;     if ((++_sp & 255u) == 0u) { if (xb_ld(&(bar)[XB_TMO])) break; if (_sp > XB_SPIN_CAP) { atomicAdd(&(bar)[XB_TMO], 1u); break; } } } } while (0)
; DI void xcd_barrier(const XcdBarrier& b) {
;     ...
;             else XB_SPIN(xb_ld(&bar[XB_TOPGEN]) == tg, bar);
;             __builtin_amdgcn_fence(__ATOMIC_ACQUIRE, "agent");
;             xb_add(&bar[XB_XGEN(b.x)], 1u);
;             asm volatile("s_waitcnt vmcnt(0)" ::: "memory");
;         } else {
;             XB_SPIN(xb_ld(&bar[XB_XGEN(b.x)]) == gen, bar);
.LBB0_474:
	s_and_b32 s34, s38, 0xff
	s_mov_b64 s[30:31], -1
	s_cmp_lg_u32 s34, 0
	s_mov_b64 s[36:37], -1
	s_nop 0
	s_cbranch_scc1 .LBB0_477
	global_load_dword v2, v0, s[10:11] sc1
	s_waitcnt vmcnt(0)
	v_cmp_eq_u32_e32 vcc, 0, v2
	s_cbranch_vccnz .LBB0_479
	s_mov_b64 s[36:37], 0
	s_mov_b64 s[34:35], -1

; DI unsigned xb_ld(unsigned* p)              { return __hip_atomic_load(p, __ATOMIC_RELAXED, __HIP_MEMORY_SCOPE_AGENT); }
; DI unsigned xb_add(unsigned* p, unsigned v) { return __hip_atomic_fetch_add(p, v, __ATOMIC_RELAXED, __HIP_MEMORY_SCOPE_AGENT); }
; #define XB_SPIN(cond, bar) do { unsigned _sp = 0; while (cond) { __builtin_amdgcn_s_sleep(1); \
;     if ((++_sp & 255u) == 0u) { if (xb_ld(&(bar)[XB_TMO])) break; if (_sp > XB_SPIN_CAP) { atomicAdd(&(bar)[XB_TMO], 1u); break; } } } } while (0)
; DI void xcd_barrier(const XcdBarrier& b) {
;     ...
;             else XB_SPIN(xb_ld(&bar[XB_TOPGEN]) == tg, bar);
;             __builtin_amdgcn_fence(__ATOMIC_ACQUIRE, "agent");
;             xb_add(&bar[XB_XGEN(b.x)], 1u);
;             asm volatile("s_waitcnt vmcnt(0)" ::: "memory");
;         } else {
;             XB_SPIN(xb_ld(&bar[XB_XGEN(b.x)]) == gen, bar);
.LBB0_491:
	s_and_b32 s30, s38, 0xff
	s_cmp_lg_u32 s30, 0
	s_mov_b64 s[34:35], -1
	s_nop 0
	s_cbranch_scc1 .LBB0_494
	global_load_dword v1, v0, s[10:11] sc1
	s_waitcnt vmcnt(0)
	v_cmp_eq_u32_e32 vcc, 0, v1
	s_cbranch_vccnz .LBB0_496
	s_mov_b64 s[34:35], 0
	s_mov_b64 s[30:31], -1

; DI unsigned xb_ld(unsigned* p)              { return __hip_atomic_load(p, __ATOMIC_RELAXED, __HIP_MEMORY_SCOPE_AGENT); }
; DI void xcd_barrier_complete(unsigned* bar, unsigned x, unsigned& nloc, unsigned& nx) {
;     ...
;     for (;;) {
;         sum = 0u; cnt = 0u; mine = 0u;
; #pragma unroll
;         for (unsigned j = 0; j < 16; ++j) { const unsigned c = xb_ld(&bar[XB_XCNT(j)]); sum += c; cnt += (c > 0u) ? 1u : 0u; mine = (j == x) ? c : mine; }
;         if (sum == G) break;
;         __builtin_amdgcn_s_sleep(1);
;         if ((++sp & 255u) == 0u) { if (xb_ld(&bar[XB_TMO])) break; if (sp > XB_SPIN_CAP) { atomicAdd(&bar[XB_TMO], 1u); break; } }
;     }
.LBB0_579:
	global_load_dword v15, v16, s[4:5] sc1
	global_load_dword v0, v16, s[6:7] sc1
	global_load_dword v1, v16, s[8:9] sc1
	global_load_dword v2, v16, s[10:11] sc1
	global_load_dword v3, v16, s[12:13] sc1
	global_load_dword v4, v16, s[14:15] sc1
	global_load_dword v5, v16, s[28:29] sc1
	global_load_dword v6, v16, s[30:31] sc1
	global_load_dword v7, v16, s[34:35] sc1
	global_load_dword v8, v16, s[36:37] sc1
	global_load_dword v9, v16, s[38:39] sc1
	global_load_dword v10, v16, s[40:41] sc1
	global_load_dword v11, v16, s[42:43] sc1
	global_load_dword v12, v16, s[44:45] sc1
	global_load_dword v13, v16, s[46:47] sc1
	global_load_dword v14, v16, s[48:49] sc1
	s_mov_b64 s[50:51], -1
	s_mov_b64 s[54:55], -1
	s_waitcnt vmcnt(14)
	v_add_u32_e32 v17, v0, v15
	s_waitcnt vmcnt(13)
	v_add_u32_e32 v17, v17, v1
	s_waitcnt vmcnt(12)
	v_add_u32_e32 v17, v17, v2
	s_waitcnt vmcnt(11)
	v_add_u32_e32 v17, v17, v3
	s_waitcnt vmcnt(10)
	v_add_u32_e32 v17, v17, v4
	s_waitcnt vmcnt(9)
	v_add_u32_e32 v17, v17, v5
	s_waitcnt vmcnt(8)
	v_add_u32_e32 v17, v17, v6
	s_waitcnt vmcnt(7)
	v_add_u32_e32 v17, v17, v7
	s_waitcnt vmcnt(6)
	v_add_u32_e32 v17, v17, v8
	s_waitcnt vmcnt(5)
	v_add_u32_e32 v17, v17, v9
	s_waitcnt vmcnt(4)
	v_add_u32_e32 v17, v17, v10
	s_waitcnt vmcnt(3)
	v_add_u32_e32 v17, v17, v11
	s_waitcnt vmcnt(2)
	v_add_u32_e32 v17, v17, v12
	s_waitcnt vmcnt(1)
	v_add_u32_e32 v17, v17, v13
	s_waitcnt vmcnt(0)
	v_add_u32_e32 v17, v17, v14
	v_cmp_eq_u32_e32 vcc, s59, v17
	s_cbranch_vccnz .LBB0_578
	s_and_b32 s50, s58, 0xff
	s_cmp_eq_u32 s50, 0
	s_mov_b64 s[50:51], -1
	s_mov_b64 s[56:57], -1
	s_nop 0
	s_cbranch_scc0 .LBB0_583
	global_load_dword v17, v16, s[2:3] sc1
	s_waitcnt vmcnt(0)
	v_cmp_eq_u32_e32 vcc, 0, v17
	s_cbranch_vccnz .LBB0_585
	s_mov_b64 s[56:57], 0

; DI unsigned xb_ld(unsigned* p)              { return __hip_atomic_load(p, __ATOMIC_RELAXED, __HIP_MEMORY_SCOPE_AGENT); }
; DI void xcd_barrier_complete(unsigned* bar, unsigned x, unsigned& nloc, unsigned& nx) {
;     ...
;     for (;;) {
;         sum = 0u; cnt = 0u; mine = 0u;
; #pragma unroll
;         for (unsigned j = 0; j < 16; ++j) { const unsigned c = xb_ld(&bar[XB_XCNT(j)]); sum += c; cnt += (c > 0u) ? 1u : 0u; mine = (j == x) ? c : mine; }
;         if (sum == G) break;
;         __builtin_amdgcn_s_sleep(1);
;         if ((++sp & 255u) == 0u) { if (xb_ld(&bar[XB_TMO])) break; if (sp > XB_SPIN_CAP) { atomicAdd(&bar[XB_TMO], 1u); break; } }
;     }
.LBB0_706:
	global_load_dword v15, v16, s[4:5] sc1
	global_load_dword v0, v16, s[6:7] sc1
	global_load_dword v1, v16, s[8:9] sc1
	global_load_dword v2, v16, s[10:11] sc1
	global_load_dword v3, v16, s[12:13] sc1
	global_load_dword v4, v16, s[14:15] sc1
	global_load_dword v5, v16, s[28:29] sc1
	global_load_dword v6, v16, s[30:31] sc1
	global_load_dword v7, v16, s[34:35] sc1
	global_load_dword v8, v16, s[36:37] sc1
	global_load_dword v9, v16, s[38:39] sc1
	global_load_dword v10, v16, s[40:41] sc1
	global_load_dword v11, v16, s[42:43] sc1
	global_load_dword v12, v16, s[44:45] sc1
	global_load_dword v13, v16, s[46:47] sc1
	global_load_dword v14, v16, s[48:49] sc1
	s_mov_b64 s[50:51], -1
	s_mov_b64 s[52:53], -1
	s_waitcnt vmcnt(14)
	v_add_u32_e32 v17, v0, v15
	s_waitcnt vmcnt(13)
	v_add_u32_e32 v17, v17, v1
	s_waitcnt vmcnt(12)
	v_add_u32_e32 v17, v17, v2
	s_waitcnt vmcnt(11)
	v_add_u32_e32 v17, v17, v3
	s_waitcnt vmcnt(10)
	v_add_u32_e32 v17, v17, v4
	s_waitcnt vmcnt(9)
	v_add_u32_e32 v17, v17, v5
	s_waitcnt vmcnt(8)
	v_add_u32_e32 v17, v17, v6
	s_waitcnt vmcnt(7)
	v_add_u32_e32 v17, v17, v7
	s_waitcnt vmcnt(6)
	v_add_u32_e32 v17, v17, v8
	s_waitcnt vmcnt(5)
	v_add_u32_e32 v17, v17, v9
	s_waitcnt vmcnt(4)
	v_add_u32_e32 v17, v17, v10
	s_waitcnt vmcnt(3)
	v_add_u32_e32 v17, v17, v11
	s_waitcnt vmcnt(2)
	v_add_u32_e32 v17, v17, v12
	s_waitcnt vmcnt(1)
	v_add_u32_e32 v17, v17, v13
	s_waitcnt vmcnt(0)
	v_add_u32_e32 v17, v17, v14
	v_cmp_eq_u32_e32 vcc, s56, v17
	s_cbranch_vccnz .LBB0_705
	s_and_b32 s50, s26, 0xff
	s_cmp_eq_u32 s50, 0
	s_mov_b64 s[50:51], -1
	s_mov_b64 s[54:55], -1
	s_nop 0
	s_cbranch_scc0 .LBB0_710
	global_load_dword v17, v16, s[2:3] sc1
	s_waitcnt vmcnt(0)
	v_cmp_eq_u32_e32 vcc, 0, v17
	s_cbranch_vccnz .LBB0_712
	s_mov_b64 s[54:55], 0

; DI unsigned xb_ld(unsigned* p)              { return __hip_atomic_load(p, __ATOMIC_RELAXED, __HIP_MEMORY_SCOPE_AGENT); }
; DI unsigned xb_add(unsigned* p, unsigned v) { return __hip_atomic_fetch_add(p, v, __ATOMIC_RELAXED, __HIP_MEMORY_SCOPE_AGENT); }
; #define XB_SPIN(cond, bar) do { unsigned _sp = 0; while (cond) { __builtin_amdgcn_s_sleep(1); \
;     if ((++_sp & 255u) == 0u) { if (xb_ld(&(bar)[XB_TMO])) break; if (_sp > XB_SPIN_CAP) { atomicAdd(&(bar)[XB_TMO], 1u); break; } } } } while (0)
; DI void xcd_barrier(const XcdBarrier& b) {
;     ...
;             else XB_SPIN(xb_ld(&bar[XB_TOPGEN]) == tg, bar);
;             __builtin_amdgcn_fence(__ATOMIC_ACQUIRE, "agent");
;             xb_add(&bar[XB_XGEN(b.x)], 1u);
;             asm volatile("s_waitcnt vmcnt(0)" ::: "memory");
;         } else {
;             XB_SPIN(xb_ld(&bar[XB_XGEN(b.x)]) == gen, bar);
.LBB0_724:
	s_and_b32 s30, s26, 0xff
	s_mov_b64 s[28:29], -1
	s_cmp_lg_u32 s30, 0
	s_mov_b64 s[34:35], -1
	s_nop 0
	s_cbranch_scc1 .LBB0_727
	global_load_dword v2, v0, s[8:9] sc1
	s_waitcnt vmcnt(0)
	v_cmp_eq_u32_e32 vcc, 0, v2
	s_cbranch_vccnz .LBB0_729
	s_mov_b64 s[34:35], 0
	s_mov_b64 s[30:31], -1

; DI unsigned xb_ld(unsigned* p)              { return __hip_atomic_load(p, __ATOMIC_RELAXED, __HIP_MEMORY_SCOPE_AGENT); }
; DI unsigned xb_add(unsigned* p, unsigned v) { return __hip_atomic_fetch_add(p, v, __ATOMIC_RELAXED, __HIP_MEMORY_SCOPE_AGENT); }
; #define XB_SPIN(cond, bar) do { unsigned _sp = 0; while (cond) { __builtin_amdgcn_s_sleep(1); \
;     if ((++_sp & 255u) == 0u) { if (xb_ld(&(bar)[XB_TMO])) break; if (_sp > XB_SPIN_CAP) { atomicAdd(&(bar)[XB_TMO], 1u); break; } } } } while (0)
; DI void xcd_barrier(const XcdBarrier& b) {
;     ...
;             else XB_SPIN(xb_ld(&bar[XB_TOPGEN]) == tg, bar);
;             __builtin_amdgcn_fence(__ATOMIC_ACQUIRE, "agent");
;             xb_add(&bar[XB_XGEN(b.x)], 1u);
;             asm volatile("s_waitcnt vmcnt(0)" ::: "memory");
;         } else {
;             XB_SPIN(xb_ld(&bar[XB_XGEN(b.x)]) == gen, bar);
.LBB0_741:
	s_and_b32 s28, s26, 0xff
	s_cmp_lg_u32 s28, 0
	s_mov_b64 s[30:31], -1
	s_nop 0
	s_cbranch_scc1 .LBB0_744
	global_load_dword v1, v0, s[8:9] sc1
	s_waitcnt vmcnt(0)
	v_cmp_eq_u32_e32 vcc, 0, v1
	s_cbranch_vccnz .LBB0_746
	s_mov_b64 s[30:31], 0
	s_mov_b64 s[28:29], -1

; DI unsigned xb_ld(unsigned* p)              { return __hip_atomic_load(p, __ATOMIC_RELAXED, __HIP_MEMORY_SCOPE_AGENT); }
; DI void xcd_barrier_complete(unsigned* bar, unsigned x, unsigned& nloc, unsigned& nx) {
;     ...
;     for (;;) {
;         sum = 0u; cnt = 0u; mine = 0u;
; #pragma unroll
;         for (unsigned j = 0; j < 16; ++j) { const unsigned c = xb_ld(&bar[XB_XCNT(j)]); sum += c; cnt += (c > 0u) ? 1u : 0u; mine = (j == x) ? c : mine; }
;         if (sum == G) break;
;         __builtin_amdgcn_s_sleep(1);
;         if ((++sp & 255u) == 0u) { if (xb_ld(&bar[XB_TMO])) break; if (sp > XB_SPIN_CAP) { atomicAdd(&bar[XB_TMO], 1u); break; } }
;     }
.LBB0_897:
	global_load_dword v15, v16, s[4:5] sc1
	s_waitcnt lgkmcnt(0)
	global_load_dword v0, v16, s[6:7] sc1
	global_load_dword v1, v16, s[8:9] sc1
	global_load_dword v2, v16, s[10:11] sc1
	global_load_dword v3, v16, s[12:13] sc1
	global_load_dword v4, v16, s[14:15] sc1
	global_load_dword v5, v16, s[30:31] sc1
	global_load_dword v6, v16, s[34:35] sc1
	global_load_dword v7, v16, s[36:37] sc1
	global_load_dword v8, v16, s[38:39] sc1
	global_load_dword v9, v16, s[40:41] sc1
	global_load_dword v10, v16, s[42:43] sc1
	global_load_dword v11, v16, s[44:45] sc1
	global_load_dword v12, v16, s[46:47] sc1
	global_load_dword v13, v16, s[48:49] sc1
	global_load_dword v14, v16, s[50:51] sc1
	s_mov_b64 s[52:53], -1
	s_mov_b64 s[54:55], -1
	s_waitcnt vmcnt(14)
	v_add_u32_e32 v17, v0, v15
	s_waitcnt vmcnt(13)
	v_add_u32_e32 v17, v17, v1
	s_waitcnt vmcnt(12)
	v_add_u32_e32 v17, v17, v2
	s_waitcnt vmcnt(11)
	v_add_u32_e32 v17, v17, v3
	s_waitcnt vmcnt(10)
	v_add_u32_e32 v17, v17, v4
	s_waitcnt vmcnt(9)
	v_add_u32_e32 v17, v17, v5
	s_waitcnt vmcnt(8)
	v_add_u32_e32 v17, v17, v6
	s_waitcnt vmcnt(7)
	v_add_u32_e32 v17, v17, v7
	s_waitcnt vmcnt(6)
	v_add_u32_e32 v17, v17, v8
	s_waitcnt vmcnt(5)
	v_add_u32_e32 v17, v17, v9
	s_waitcnt vmcnt(4)
	v_add_u32_e32 v17, v17, v10
	s_waitcnt vmcnt(3)
	v_add_u32_e32 v17, v17, v11
	s_waitcnt vmcnt(2)
	v_add_u32_e32 v17, v17, v12
	s_waitcnt vmcnt(1)
	v_add_u32_e32 v17, v17, v13
	s_waitcnt vmcnt(0)
	v_add_u32_e32 v17, v17, v14
	v_cmp_eq_u32_e32 vcc, s26, v17
	s_cbranch_vccnz .LBB0_896
	s_and_b32 s52, s58, 0xff
	s_cmp_eq_u32 s52, 0
	s_mov_b64 s[52:53], -1
	s_mov_b64 s[56:57], -1
	s_nop 0
	s_cbranch_scc0 .LBB0_901
	global_load_dword v17, v16, s[2:3] sc1
	s_waitcnt vmcnt(0)
	v_cmp_eq_u32_e32 vcc, 0, v17
	s_cbranch_vccnz .LBB0_903
	s_mov_b64 s[56:57], 0

; DI unsigned xb_ld(unsigned* p)              { return __hip_atomic_load(p, __ATOMIC_RELAXED, __HIP_MEMORY_SCOPE_AGENT); }
; DI unsigned xb_add(unsigned* p, unsigned v) { return __hip_atomic_fetch_add(p, v, __ATOMIC_RELAXED, __HIP_MEMORY_SCOPE_AGENT); }
; #define XB_SPIN(cond, bar) do { unsigned _sp = 0; while (cond) { __builtin_amdgcn_s_sleep(1); \
;     if ((++_sp & 255u) == 0u) { if (xb_ld(&(bar)[XB_TMO])) break; if (_sp > XB_SPIN_CAP) { atomicAdd(&(bar)[XB_TMO], 1u); break; } } } } while (0)
; DI void xcd_barrier(const XcdBarrier& b) {
;     ...
;             else XB_SPIN(xb_ld(&bar[XB_TOPGEN]) == tg, bar);
;             __builtin_amdgcn_fence(__ATOMIC_ACQUIRE, "agent");
;             xb_add(&bar[XB_XGEN(b.x)], 1u);
;             asm volatile("s_waitcnt vmcnt(0)" ::: "memory");
;         } else {
;             XB_SPIN(xb_ld(&bar[XB_XGEN(b.x)]) == gen, bar);
.LBB0_915:
	s_and_b32 s34, s26, 0xff
	s_mov_b64 s[30:31], -1
	s_cmp_lg_u32 s34, 0
	s_mov_b64 s[36:37], -1
	s_nop 0
	s_cbranch_scc1 .LBB0_918
	global_load_dword v2, v0, s[8:9] sc1
	s_waitcnt vmcnt(0)
	v_cmp_eq_u32_e32 vcc, 0, v2
	s_cbranch_vccnz .LBB0_920
	s_mov_b64 s[36:37], 0
	s_mov_b64 s[34:35], -1

; DI unsigned xb_ld(unsigned* p)              { return __hip_atomic_load(p, __ATOMIC_RELAXED, __HIP_MEMORY_SCOPE_AGENT); }
; DI unsigned xb_add(unsigned* p, unsigned v) { return __hip_atomic_fetch_add(p, v, __ATOMIC_RELAXED, __HIP_MEMORY_SCOPE_AGENT); }
; #define XB_SPIN(cond, bar) do { unsigned _sp = 0; while (cond) { __builtin_amdgcn_s_sleep(1); \
;     if ((++_sp & 255u) == 0u) { if (xb_ld(&(bar)[XB_TMO])) break; if (_sp > XB_SPIN_CAP) { atomicAdd(&(bar)[XB_TMO], 1u); break; } } } } while (0)
; DI void xcd_barrier(const XcdBarrier& b) {
;     ...
;             else XB_SPIN(xb_ld(&bar[XB_TOPGEN]) == tg, bar);
;             __builtin_amdgcn_fence(__ATOMIC_ACQUIRE, "agent");
;             xb_add(&bar[XB_XGEN(b.x)], 1u);
;             asm volatile("s_waitcnt vmcnt(0)" ::: "memory");
;         } else {
;             XB_SPIN(xb_ld(&bar[XB_XGEN(b.x)]) == gen, bar);
.LBB0_932:
	s_and_b32 s30, s26, 0xff
	s_cmp_lg_u32 s30, 0
	s_mov_b64 s[34:35], -1
	s_nop 0
	s_cbranch_scc1 .LBB0_935
	global_load_dword v1, v0, s[8:9] sc1
	s_waitcnt vmcnt(0)
	v_cmp_eq_u32_e32 vcc, 0, v1
	s_cbranch_vccnz .LBB0_937
	s_mov_b64 s[34:35], 0
	s_mov_b64 s[30:31], -1

; DI unsigned xb_ld(unsigned* p)              { return __hip_atomic_load(p, __ATOMIC_RELAXED, __HIP_MEMORY_SCOPE_AGENT); }
; DI void xcd_barrier_complete(unsigned* bar, unsigned x, unsigned& nloc, unsigned& nx) {
;     ...
;     for (;;) {
;         sum = 0u; cnt = 0u; mine = 0u;
; #pragma unroll
;         for (unsigned j = 0; j < 16; ++j) { const unsigned c = xb_ld(&bar[XB_XCNT(j)]); sum += c; cnt += (c > 0u) ? 1u : 0u; mine = (j == x) ? c : mine; }
;         if (sum == G) break;
;         __builtin_amdgcn_s_sleep(1);
;         if ((++sp & 255u) == 0u) { if (xb_ld(&bar[XB_TMO])) break; if (sp > XB_SPIN_CAP) { atomicAdd(&bar[XB_TMO], 1u); break; } }
;     }
.LBB0_1034:
	global_load_dword v15, v16, s[4:5] sc1
	global_load_dword v0, v16, s[8:9] sc1
	global_load_dword v1, v16, s[10:11] sc1
	global_load_dword v2, v16, s[12:13] sc1
	global_load_dword v3, v16, s[14:15] sc1
	global_load_dword v4, v16, s[30:31] sc1
	global_load_dword v5, v16, s[34:35] sc1
	global_load_dword v6, v16, s[36:37] sc1
	global_load_dword v7, v16, s[38:39] sc1
	global_load_dword v8, v16, s[40:41] sc1
	global_load_dword v9, v16, s[42:43] sc1
	global_load_dword v10, v16, s[44:45] sc1
	global_load_dword v11, v16, s[46:47] sc1
	global_load_dword v12, v16, s[48:49] sc1
	global_load_dword v13, v16, s[50:51] sc1
	global_load_dword v14, v16, s[52:53] sc1
	s_mov_b64 s[54:55], -1
	s_mov_b64 s[56:57], -1
	s_waitcnt vmcnt(14)
	v_add_u32_e32 v17, v0, v15
	s_waitcnt vmcnt(13)
	v_add_u32_e32 v17, v17, v1
	s_waitcnt vmcnt(12)
	v_add_u32_e32 v17, v17, v2
	s_waitcnt vmcnt(11)
	v_add_u32_e32 v17, v17, v3
	s_waitcnt vmcnt(10)
	v_add_u32_e32 v17, v17, v4
	s_waitcnt vmcnt(9)
	v_add_u32_e32 v17, v17, v5
	s_waitcnt vmcnt(8)
	v_add_u32_e32 v17, v17, v6
	s_waitcnt vmcnt(7)
	v_add_u32_e32 v17, v17, v7
	s_waitcnt vmcnt(6)
	v_add_u32_e32 v17, v17, v8
	s_waitcnt vmcnt(5)
	v_add_u32_e32 v17, v17, v9
	s_waitcnt vmcnt(4)
	v_add_u32_e32 v17, v17, v10
	s_waitcnt vmcnt(3)
	v_add_u32_e32 v17, v17, v11
	s_waitcnt vmcnt(2)
	v_add_u32_e32 v17, v17, v12
	s_waitcnt vmcnt(1)
	v_add_u32_e32 v17, v17, v13
	s_waitcnt vmcnt(0)
	v_add_u32_e32 v17, v17, v14
	v_cmp_eq_u32_e32 vcc, s7, v17
	s_cbranch_vccnz .LBB0_1033
	s_and_b32 s54, s71, 0xff
	s_cmp_eq_u32 s54, 0
	s_mov_b64 s[54:55], -1
	s_mov_b64 s[58:59], -1
	s_nop 0
	s_cbranch_scc0 .LBB0_1038
	global_load_dword v17, v16, s[2:3] sc1
	s_waitcnt vmcnt(0)
	v_cmp_eq_u32_e32 vcc, 0, v17
	s_cbranch_vccnz .LBB0_1040
	s_mov_b64 s[58:59], 0

; DI unsigned xb_ld(unsigned* p)              { return __hip_atomic_load(p, __ATOMIC_RELAXED, __HIP_MEMORY_SCOPE_AGENT); }
; DI unsigned xb_add(unsigned* p, unsigned v) { return __hip_atomic_fetch_add(p, v, __ATOMIC_RELAXED, __HIP_MEMORY_SCOPE_AGENT); }
; #define XB_SPIN(cond, bar) do { unsigned _sp = 0; while (cond) { __builtin_amdgcn_s_sleep(1); \
;     if ((++_sp & 255u) == 0u) { if (xb_ld(&(bar)[XB_TMO])) break; if (_sp > XB_SPIN_CAP) { atomicAdd(&(bar)[XB_TMO], 1u); break; } } } } while (0)
; DI void xcd_barrier(const XcdBarrier& b) {
;     ...
;             else XB_SPIN(xb_ld(&bar[XB_TOPGEN]) == tg, bar);
;             __builtin_amdgcn_fence(__ATOMIC_ACQUIRE, "agent");
;             xb_add(&bar[XB_XGEN(b.x)], 1u);
;             asm volatile("s_waitcnt vmcnt(0)" ::: "memory");
;         } else {
;             XB_SPIN(xb_ld(&bar[XB_XGEN(b.x)]) == gen, bar);
.LBB0_1052:
	s_and_b32 s36, s7, 0xff
	s_mov_b64 s[34:35], -1
	s_cmp_lg_u32 s36, 0
	s_mov_b64 s[38:39], -1
	s_nop 0
	s_cbranch_scc1 .LBB0_1055
	global_load_dword v2, v0, s[10:11] sc1
	s_waitcnt vmcnt(0)
	v_cmp_eq_u32_e32 vcc, 0, v2
	s_cbranch_vccnz .LBB0_1057
	s_mov_b64 s[38:39], 0
	s_mov_b64 s[36:37], -1

; DI unsigned xb_ld(unsigned* p)              { return __hip_atomic_load(p, __ATOMIC_RELAXED, __HIP_MEMORY_SCOPE_AGENT); }
; DI unsigned xb_add(unsigned* p, unsigned v) { return __hip_atomic_fetch_add(p, v, __ATOMIC_RELAXED, __HIP_MEMORY_SCOPE_AGENT); }
; #define XB_SPIN(cond, bar) do { unsigned _sp = 0; while (cond) { __builtin_amdgcn_s_sleep(1); \
;     if ((++_sp & 255u) == 0u) { if (xb_ld(&(bar)[XB_TMO])) break; if (_sp > XB_SPIN_CAP) { atomicAdd(&(bar)[XB_TMO], 1u); break; } } } } while (0)
; DI void xcd_barrier(const XcdBarrier& b) {
;     ...
;             else XB_SPIN(xb_ld(&bar[XB_TOPGEN]) == tg, bar);
;             __builtin_amdgcn_fence(__ATOMIC_ACQUIRE, "agent");
;             xb_add(&bar[XB_XGEN(b.x)], 1u);
;             asm volatile("s_waitcnt vmcnt(0)" ::: "memory");
;         } else {
;             XB_SPIN(xb_ld(&bar[XB_XGEN(b.x)]) == gen, bar);
.LBB0_1069:
	s_and_b32 s34, s7, 0xff
	s_cmp_lg_u32 s34, 0
	s_mov_b64 s[36:37], -1
	s_nop 0
	s_cbranch_scc1 .LBB0_1072
	global_load_dword v1, v0, s[10:11] sc1
	s_waitcnt vmcnt(0)
	v_cmp_eq_u32_e32 vcc, 0, v1
	s_cbranch_vccnz .LBB0_1074
	s_mov_b64 s[36:37], 0
	s_mov_b64 s[34:35], -1

; DI unsigned xb_ld(unsigned* p)              { return __hip_atomic_load(p, __ATOMIC_RELAXED, __HIP_MEMORY_SCOPE_AGENT); }
; DI void xcd_barrier_complete(unsigned* bar, unsigned x, unsigned& nloc, unsigned& nx) {
;     ...
;     for (;;) {
;         sum = 0u; cnt = 0u; mine = 0u;
; #pragma unroll
;         for (unsigned j = 0; j < 16; ++j) { const unsigned c = xb_ld(&bar[XB_XCNT(j)]); sum += c; cnt += (c > 0u) ? 1u : 0u; mine = (j == x) ? c : mine; }
;         if (sum == G) break;
;         __builtin_amdgcn_s_sleep(1);
;         if ((++sp & 255u) == 0u) { if (xb_ld(&bar[XB_TMO])) break; if (sp > XB_SPIN_CAP) { atomicAdd(&bar[XB_TMO], 1u); break; } }
;     }
.LBB0_1114:
	global_load_dword v15, v16, s[4:5] sc1
	global_load_dword v0, v16, s[10:11] sc1
	global_load_dword v1, v16, s[12:13] sc1
	global_load_dword v2, v16, s[14:15] sc1
	global_load_dword v3, v16, s[30:31] sc1
	global_load_dword v4, v16, s[34:35] sc1
	global_load_dword v5, v16, s[36:37] sc1
	global_load_dword v6, v16, s[38:39] sc1
	global_load_dword v7, v16, s[40:41] sc1
	global_load_dword v8, v16, s[42:43] sc1
	global_load_dword v9, v16, s[44:45] sc1
	global_load_dword v10, v16, s[46:47] sc1
	global_load_dword v11, v16, s[48:49] sc1
	global_load_dword v12, v16, s[50:51] sc1
	global_load_dword v13, v16, s[52:53] sc1
	global_load_dword v14, v16, s[54:55] sc1
	s_mov_b64 s[56:57], -1
	s_mov_b64 s[58:59], -1
	s_waitcnt vmcnt(14)
	v_add_u32_e32 v17, v0, v15
	s_waitcnt vmcnt(13)
	v_add_u32_e32 v17, v17, v1
	s_waitcnt vmcnt(12)
	v_add_u32_e32 v17, v17, v2
	s_waitcnt vmcnt(11)
	v_add_u32_e32 v17, v17, v3
	s_waitcnt vmcnt(10)
	v_add_u32_e32 v17, v17, v4
	s_waitcnt vmcnt(9)
	v_add_u32_e32 v17, v17, v5
	s_waitcnt vmcnt(8)
	v_add_u32_e32 v17, v17, v6
	s_waitcnt vmcnt(7)
	v_add_u32_e32 v17, v17, v7
	s_waitcnt vmcnt(6)
	v_add_u32_e32 v17, v17, v8
	s_waitcnt vmcnt(5)
	v_add_u32_e32 v17, v17, v9
	s_waitcnt vmcnt(4)
	v_add_u32_e32 v17, v17, v10
	s_waitcnt vmcnt(3)
	v_add_u32_e32 v17, v17, v11
	s_waitcnt vmcnt(2)
	v_add_u32_e32 v17, v17, v12
	s_waitcnt vmcnt(1)
	v_add_u32_e32 v17, v17, v13
	s_waitcnt vmcnt(0)
	v_add_u32_e32 v17, v17, v14
	v_cmp_eq_u32_e32 vcc, s7, v17
	s_cbranch_vccnz .LBB0_1113
	s_and_b32 s56, s71, 0xff
	s_cmp_eq_u32 s56, 0
	s_mov_b64 s[56:57], -1
	s_mov_b64 s[72:73], -1
	s_nop 0
	s_cbranch_scc0 .LBB0_1118
	global_load_dword v17, v16, s[2:3] sc1
	s_waitcnt vmcnt(0)
	v_cmp_eq_u32_e32 vcc, 0, v17
	s_cbranch_vccnz .LBB0_1120
	s_mov_b64 s[72:73], 0

; DI unsigned xb_ld(unsigned* p)              { return __hip_atomic_load(p, __ATOMIC_RELAXED, __HIP_MEMORY_SCOPE_AGENT); }
; DI unsigned xb_add(unsigned* p, unsigned v) { return __hip_atomic_fetch_add(p, v, __ATOMIC_RELAXED, __HIP_MEMORY_SCOPE_AGENT); }
; #define XB_SPIN(cond, bar) do { unsigned _sp = 0; while (cond) { __builtin_amdgcn_s_sleep(1); \
;     if ((++_sp & 255u) == 0u) { if (xb_ld(&(bar)[XB_TMO])) break; if (_sp > XB_SPIN_CAP) { atomicAdd(&(bar)[XB_TMO], 1u); break; } } } } while (0)
; DI void xcd_barrier(const XcdBarrier& b) {
;     ...
;             else XB_SPIN(xb_ld(&bar[XB_TOPGEN]) == tg, bar);
;             __builtin_amdgcn_fence(__ATOMIC_ACQUIRE, "agent");
;             xb_add(&bar[XB_XGEN(b.x)], 1u);
;             asm volatile("s_waitcnt vmcnt(0)" ::: "memory");
;         } else {
;             XB_SPIN(xb_ld(&bar[XB_XGEN(b.x)]) == gen, bar);
.LBB0_1132:
	s_and_b32 s38, s7, 0xff
	s_mov_b64 s[36:37], -1
	s_cmp_lg_u32 s38, 0
	s_mov_b64 s[40:41], -1
	s_nop 0
	s_cbranch_scc1 .LBB0_1135
	global_load_dword v2, v0, s[12:13] sc1
	s_waitcnt vmcnt(0)
	v_cmp_eq_u32_e32 vcc, 0, v2
	s_cbranch_vccnz .LBB0_1137
	s_mov_b64 s[40:41], 0
	s_mov_b64 s[38:39], -1

; DI unsigned xb_ld(unsigned* p)              { return __hip_atomic_load(p, __ATOMIC_RELAXED, __HIP_MEMORY_SCOPE_AGENT); }
; DI unsigned xb_add(unsigned* p, unsigned v) { return __hip_atomic_fetch_add(p, v, __ATOMIC_RELAXED, __HIP_MEMORY_SCOPE_AGENT); }
; #define XB_SPIN(cond, bar) do { unsigned _sp = 0; while (cond) { __builtin_amdgcn_s_sleep(1); \
;     if ((++_sp & 255u) == 0u) { if (xb_ld(&(bar)[XB_TMO])) break; if (_sp > XB_SPIN_CAP) { atomicAdd(&(bar)[XB_TMO], 1u); break; } } } } while (0)
; DI void xcd_barrier(const XcdBarrier& b) {
;     ...
;             else XB_SPIN(xb_ld(&bar[XB_TOPGEN]) == tg, bar);
;             __builtin_amdgcn_fence(__ATOMIC_ACQUIRE, "agent");
;             xb_add(&bar[XB_XGEN(b.x)], 1u);
;             asm volatile("s_waitcnt vmcnt(0)" ::: "memory");
;         } else {
;             XB_SPIN(xb_ld(&bar[XB_XGEN(b.x)]) == gen, bar);
.LBB0_1149:
	s_and_b32 s36, s7, 0xff
	s_cmp_lg_u32 s36, 0
	s_mov_b64 s[38:39], -1
	s_nop 0
	s_cbranch_scc1 .LBB0_1152
	global_load_dword v1, v0, s[12:13] sc1
	s_waitcnt vmcnt(0)
	v_cmp_eq_u32_e32 vcc, 0, v1
	s_cbranch_vccnz .LBB0_1154
	s_mov_b64 s[38:39], 0
	s_mov_b64 s[36:37], -1

; DI unsigned xb_ld(unsigned* p)              { return __hip_atomic_load(p, __ATOMIC_RELAXED, __HIP_MEMORY_SCOPE_AGENT); }
; DI void xcd_barrier_complete(unsigned* bar, unsigned x, unsigned& nloc, unsigned& nx) {
;     ...
;     for (;;) {
;         sum = 0u; cnt = 0u; mine = 0u;
; #pragma unroll
;         for (unsigned j = 0; j < 16; ++j) { const unsigned c = xb_ld(&bar[XB_XCNT(j)]); sum += c; cnt += (c > 0u) ? 1u : 0u; mine = (j == x) ? c : mine; }
;         if (sum == G) break;
;         __builtin_amdgcn_s_sleep(1);
;         if ((++sp & 255u) == 0u) { if (xb_ld(&bar[XB_TMO])) break; if (sp > XB_SPIN_CAP) { atomicAdd(&bar[XB_TMO], 1u); break; } }
;     }
.LBB0_1235:
	global_load_dword v15, v16, s[4:5] sc1
	global_load_dword v0, v16, s[12:13] sc1
	global_load_dword v1, v16, s[14:15] sc1
	global_load_dword v2, v16, s[30:31] sc1
	global_load_dword v3, v16, s[34:35] sc1
	global_load_dword v4, v16, s[36:37] sc1
	global_load_dword v5, v16, s[38:39] sc1
	global_load_dword v6, v16, s[40:41] sc1
	global_load_dword v7, v16, s[42:43] sc1
	global_load_dword v8, v16, s[44:45] sc1
	global_load_dword v9, v16, s[46:47] sc1
	global_load_dword v10, v16, s[48:49] sc1
	global_load_dword v11, v16, s[50:51] sc1
	global_load_dword v12, v16, s[52:53] sc1
	global_load_dword v13, v16, s[54:55] sc1
	global_load_dword v14, v16, s[56:57] sc1
	s_mov_b64 s[58:59], -1
	s_mov_b64 s[72:73], -1
	s_waitcnt vmcnt(14)
	v_add_u32_e32 v17, v0, v15
	s_waitcnt vmcnt(13)
	v_add_u32_e32 v17, v17, v1
	s_waitcnt vmcnt(12)
	v_add_u32_e32 v17, v17, v2
	s_waitcnt vmcnt(11)
	v_add_u32_e32 v17, v17, v3
	s_waitcnt vmcnt(10)
	v_add_u32_e32 v17, v17, v4
	s_waitcnt vmcnt(9)
	v_add_u32_e32 v17, v17, v5
	s_waitcnt vmcnt(8)
	v_add_u32_e32 v17, v17, v6
	s_waitcnt vmcnt(7)
	v_add_u32_e32 v17, v17, v7
	s_waitcnt vmcnt(6)
	v_add_u32_e32 v17, v17, v8
	s_waitcnt vmcnt(5)
	v_add_u32_e32 v17, v17, v9
	s_waitcnt vmcnt(4)
	v_add_u32_e32 v17, v17, v10
	s_waitcnt vmcnt(3)
	v_add_u32_e32 v17, v17, v11
	s_waitcnt vmcnt(2)
	v_add_u32_e32 v17, v17, v12
	s_waitcnt vmcnt(1)
	v_add_u32_e32 v17, v17, v13
	s_waitcnt vmcnt(0)
	v_add_u32_e32 v17, v17, v14
	v_cmp_eq_u32_e32 vcc, s7, v17
	s_cbranch_vccnz .LBB0_1234
	s_and_b32 s58, s71, 0xff
	s_cmp_eq_u32 s58, 0
	s_mov_b64 s[58:59], -1
	s_mov_b64 s[74:75], -1
	s_nop 0
	s_cbranch_scc0 .LBB0_1239
	global_load_dword v17, v16, s[2:3] sc1
	s_waitcnt vmcnt(0)
	v_cmp_eq_u32_e32 vcc, 0, v17
	s_cbranch_vccnz .LBB0_1241
	s_mov_b64 s[74:75], 0

; DI unsigned xb_ld(unsigned* p)              { return __hip_atomic_load(p, __ATOMIC_RELAXED, __HIP_MEMORY_SCOPE_AGENT); }
; DI unsigned xb_add(unsigned* p, unsigned v) { return __hip_atomic_fetch_add(p, v, __ATOMIC_RELAXED, __HIP_MEMORY_SCOPE_AGENT); }
; #define XB_SPIN(cond, bar) do { unsigned _sp = 0; while (cond) { __builtin_amdgcn_s_sleep(1); \
;     if ((++_sp & 255u) == 0u) { if (xb_ld(&(bar)[XB_TMO])) break; if (_sp > XB_SPIN_CAP) { atomicAdd(&(bar)[XB_TMO], 1u); break; } } } } while (0)
; DI void xcd_barrier(const XcdBarrier& b) {
;     ...
;             else XB_SPIN(xb_ld(&bar[XB_TOPGEN]) == tg, bar);
;             __builtin_amdgcn_fence(__ATOMIC_ACQUIRE, "agent");
;             xb_add(&bar[XB_XGEN(b.x)], 1u);
;             asm volatile("s_waitcnt vmcnt(0)" ::: "memory");
;         } else {
;             XB_SPIN(xb_ld(&bar[XB_XGEN(b.x)]) == gen, bar);
.LBB0_1253:
	s_and_b32 s40, s7, 0xff
	s_mov_b64 s[38:39], -1
	s_cmp_lg_u32 s40, 0
	s_mov_b64 s[42:43], -1
	s_nop 0
	s_cbranch_scc1 .LBB0_1256
	global_load_dword v2, v0, s[14:15] sc1
	s_waitcnt vmcnt(0)
	v_cmp_eq_u32_e32 vcc, 0, v2
	s_cbranch_vccnz .LBB0_1258
	s_mov_b64 s[42:43], 0
	s_mov_b64 s[40:41], -1

; DI unsigned xb_ld(unsigned* p)              { return __hip_atomic_load(p, __ATOMIC_RELAXED, __HIP_MEMORY_SCOPE_AGENT); }
; DI unsigned xb_add(unsigned* p, unsigned v) { return __hip_atomic_fetch_add(p, v, __ATOMIC_RELAXED, __HIP_MEMORY_SCOPE_AGENT); }
; #define XB_SPIN(cond, bar) do { unsigned _sp = 0; while (cond) { __builtin_amdgcn_s_sleep(1); \
;     if ((++_sp & 255u) == 0u) { if (xb_ld(&(bar)[XB_TMO])) break; if (_sp > XB_SPIN_CAP) { atomicAdd(&(bar)[XB_TMO], 1u); break; } } } } while (0)
; DI void xcd_barrier(const XcdBarrier& b) {
;     ...
;             else XB_SPIN(xb_ld(&bar[XB_TOPGEN]) == tg, bar);
;             __builtin_amdgcn_fence(__ATOMIC_ACQUIRE, "agent");
;             xb_add(&bar[XB_XGEN(b.x)], 1u);
;             asm volatile("s_waitcnt vmcnt(0)" ::: "memory");
;         } else {
;             XB_SPIN(xb_ld(&bar[XB_XGEN(b.x)]) == gen, bar);
.LBB0_1270:
	s_and_b32 s38, s7, 0xff
	s_cmp_lg_u32 s38, 0
	s_mov_b64 s[40:41], -1
	s_nop 0
	s_cbranch_scc1 .LBB0_1273
	global_load_dword v1, v0, s[14:15] sc1
	s_waitcnt vmcnt(0)
	v_cmp_eq_u32_e32 vcc, 0, v1
	s_cbranch_vccnz .LBB0_1275
	s_mov_b64 s[40:41], 0
	s_mov_b64 s[38:39], -1

; DI unsigned xb_ld(unsigned* p)              { return __hip_atomic_load(p, __ATOMIC_RELAXED, __HIP_MEMORY_SCOPE_AGENT); }
; DI void xcd_barrier_complete(unsigned* bar, unsigned x, unsigned& nloc, unsigned& nx) {
;     ...
;     for (;;) {
;         sum = 0u; cnt = 0u; mine = 0u;
; #pragma unroll
;         for (unsigned j = 0; j < 16; ++j) { const unsigned c = xb_ld(&bar[XB_XCNT(j)]); sum += c; cnt += (c > 0u) ? 1u : 0u; mine = (j == x) ? c : mine; }
;         if (sum == G) break;
;         __builtin_amdgcn_s_sleep(1);
;         if ((++sp & 255u) == 0u) { if (xb_ld(&bar[XB_TMO])) break; if (sp > XB_SPIN_CAP) { atomicAdd(&bar[XB_TMO], 1u); break; } }
;     }
.LBB0_1637:
	global_load_dword v15, v16, s[4:5] sc1
	global_load_dword v0, v16, s[6:7] sc1
	global_load_dword v1, v16, s[8:9] sc1
	global_load_dword v2, v16, s[10:11] sc1
	global_load_dword v3, v16, s[12:13] sc1
	global_load_dword v4, v16, s[14:15] sc1
	global_load_dword v5, v16, s[30:31] sc1
	global_load_dword v6, v16, s[34:35] sc1
	global_load_dword v7, v16, s[36:37] sc1
	global_load_dword v8, v16, s[38:39] sc1
	global_load_dword v9, v16, s[40:41] sc1
	global_load_dword v10, v16, s[42:43] sc1
	global_load_dword v11, v16, s[44:45] sc1
	global_load_dword v12, v16, s[46:47] sc1
	global_load_dword v13, v16, s[48:49] sc1
	global_load_dword v14, v16, s[50:51] sc1
	s_mov_b64 s[52:53], -1
	s_mov_b64 s[54:55], -1
	s_waitcnt vmcnt(14)
	v_add_u32_e32 v17, v0, v15
	s_waitcnt vmcnt(13)
	v_add_u32_e32 v17, v17, v1
	s_waitcnt vmcnt(12)
	v_add_u32_e32 v17, v17, v2
	s_waitcnt vmcnt(11)
	v_add_u32_e32 v17, v17, v3
	s_waitcnt vmcnt(10)
	v_add_u32_e32 v17, v17, v4
	s_waitcnt vmcnt(9)
	v_add_u32_e32 v17, v17, v5
	s_waitcnt vmcnt(8)
	v_add_u32_e32 v17, v17, v6
	s_waitcnt vmcnt(7)
	v_add_u32_e32 v17, v17, v7
	s_waitcnt vmcnt(6)
	v_add_u32_e32 v17, v17, v8
	s_waitcnt vmcnt(5)
	v_add_u32_e32 v17, v17, v9
	s_waitcnt vmcnt(4)
	v_add_u32_e32 v17, v17, v10
	s_waitcnt vmcnt(3)
	v_add_u32_e32 v17, v17, v11
	s_waitcnt vmcnt(2)
	v_add_u32_e32 v17, v17, v12
	s_waitcnt vmcnt(1)
	v_add_u32_e32 v17, v17, v13
	s_waitcnt vmcnt(0)
	v_add_u32_e32 v17, v17, v14
	v_cmp_eq_u32_e32 vcc, s58, v17
	s_cbranch_vccnz .LBB0_1636
	s_and_b32 s52, s59, 0xff
	s_cmp_eq_u32 s52, 0
	s_mov_b64 s[52:53], -1
	s_mov_b64 s[56:57], -1
	s_nop 0
	s_cbranch_scc0 .LBB0_1641
	global_load_dword v17, v16, s[2:3] sc1
	s_waitcnt vmcnt(0)
	v_cmp_eq_u32_e32 vcc, 0, v17
	s_cbranch_vccnz .LBB0_1643
	s_mov_b64 s[56:57], 0

; DI unsigned xb_ld(unsigned* p)              { return __hip_atomic_load(p, __ATOMIC_RELAXED, __HIP_MEMORY_SCOPE_AGENT); }
; DI unsigned xb_add(unsigned* p, unsigned v) { return __hip_atomic_fetch_add(p, v, __ATOMIC_RELAXED, __HIP_MEMORY_SCOPE_AGENT); }
; #define XB_SPIN(cond, bar) do { unsigned _sp = 0; while (cond) { __builtin_amdgcn_s_sleep(1); \
;     if ((++_sp & 255u) == 0u) { if (xb_ld(&(bar)[XB_TMO])) break; if (_sp > XB_SPIN_CAP) { atomicAdd(&(bar)[XB_TMO], 1u); break; } } } } while (0)
; DI void xcd_barrier(const XcdBarrier& b) {
;     ...
;             else XB_SPIN(xb_ld(&bar[XB_TOPGEN]) == tg, bar);
;             __builtin_amdgcn_fence(__ATOMIC_ACQUIRE, "agent");
;             xb_add(&bar[XB_XGEN(b.x)], 1u);
;             asm volatile("s_waitcnt vmcnt(0)" ::: "memory");
;         } else {
;             XB_SPIN(xb_ld(&bar[XB_XGEN(b.x)]) == gen, bar);
.LBB0_1655:
	s_and_b32 s34, s38, 0xff
	s_mov_b64 s[30:31], -1
	s_cmp_lg_u32 s34, 0
	s_mov_b64 s[36:37], -1
	s_nop 0
	s_cbranch_scc1 .LBB0_1658
	global_load_dword v2, v0, s[8:9] sc1
	s_waitcnt vmcnt(0)
	v_cmp_eq_u32_e32 vcc, 0, v2
	s_cbranch_vccnz .LBB0_1660
	s_mov_b64 s[36:37], 0
	s_mov_b64 s[34:35], -1

; DI unsigned xb_ld(unsigned* p)              { return __hip_atomic_load(p, __ATOMIC_RELAXED, __HIP_MEMORY_SCOPE_AGENT); }
; DI unsigned xb_add(unsigned* p, unsigned v) { return __hip_atomic_fetch_add(p, v, __ATOMIC_RELAXED, __HIP_MEMORY_SCOPE_AGENT); }
; #define XB_SPIN(cond, bar) do { unsigned _sp = 0; while (cond) { __builtin_amdgcn_s_sleep(1); \
;     if ((++_sp & 255u) == 0u) { if (xb_ld(&(bar)[XB_TMO])) break; if (_sp > XB_SPIN_CAP) { atomicAdd(&(bar)[XB_TMO], 1u); break; } } } } while (0)
; DI void xcd_barrier(const XcdBarrier& b) {
;     ...
;             else XB_SPIN(xb_ld(&bar[XB_TOPGEN]) == tg, bar);
;             __builtin_amdgcn_fence(__ATOMIC_ACQUIRE, "agent");
;             xb_add(&bar[XB_XGEN(b.x)], 1u);
;             asm volatile("s_waitcnt vmcnt(0)" ::: "memory");
;         } else {
;             XB_SPIN(xb_ld(&bar[XB_XGEN(b.x)]) == gen, bar);
.LBB0_1672:
	s_and_b32 s30, s38, 0xff
	s_cmp_lg_u32 s30, 0
	s_mov_b64 s[34:35], -1
	s_nop 0
	s_cbranch_scc1 .LBB0_1675
	global_load_dword v1, v0, s[8:9] sc1
	s_waitcnt vmcnt(0)
	v_cmp_eq_u32_e32 vcc, 0, v1
	s_cbranch_vccnz .LBB0_1677
	s_mov_b64 s[34:35], 0
	s_mov_b64 s[30:31], -1

; DI unsigned xb_ld(unsigned* p)              { return __hip_atomic_load(p, __ATOMIC_RELAXED, __HIP_MEMORY_SCOPE_AGENT); }
; DI void xcd_barrier_complete(unsigned* bar, unsigned x, unsigned& nloc, unsigned& nx) {
;     ...
;     for (;;) {
;         sum = 0u; cnt = 0u; mine = 0u;
; #pragma unroll
;         for (unsigned j = 0; j < 16; ++j) { const unsigned c = xb_ld(&bar[XB_XCNT(j)]); sum += c; cnt += (c > 0u) ? 1u : 0u; mine = (j == x) ? c : mine; }
;         if (sum == G) break;
;         __builtin_amdgcn_s_sleep(1);
;         if ((++sp & 255u) == 0u) { if (xb_ld(&bar[XB_TMO])) break; if (sp > XB_SPIN_CAP) { atomicAdd(&bar[XB_TMO], 1u); break; } }
;     }
.LBB0_1828:
	global_load_dword v15, v16, s[4:5] sc1
	global_load_dword v0, v16, s[6:7] sc1
	global_load_dword v1, v16, s[8:9] sc1
	global_load_dword v2, v16, s[10:11] sc1
	global_load_dword v3, v16, s[12:13] sc1
	global_load_dword v4, v16, s[14:15] sc1
	global_load_dword v5, v16, s[30:31] sc1
	global_load_dword v6, v16, s[34:35] sc1
	global_load_dword v7, v16, s[36:37] sc1
	global_load_dword v8, v16, s[38:39] sc1
	global_load_dword v9, v16, s[40:41] sc1
	global_load_dword v10, v16, s[42:43] sc1
	global_load_dword v11, v16, s[44:45] sc1
	global_load_dword v12, v16, s[46:47] sc1
	global_load_dword v13, v16, s[48:49] sc1
	global_load_dword v14, v16, s[50:51] sc1
	s_mov_b64 s[52:53], -1
	s_mov_b64 s[54:55], -1
	s_waitcnt vmcnt(14)
	v_add_u32_e32 v17, v0, v15
	s_waitcnt vmcnt(13)
	v_add_u32_e32 v17, v17, v1
	s_waitcnt vmcnt(12)
	v_add_u32_e32 v17, v17, v2
	s_waitcnt vmcnt(11)
	v_add_u32_e32 v17, v17, v3
	s_waitcnt vmcnt(10)
	v_add_u32_e32 v17, v17, v4
	s_waitcnt vmcnt(9)
	v_add_u32_e32 v17, v17, v5
	s_waitcnt vmcnt(8)
	v_add_u32_e32 v17, v17, v6
	s_waitcnt vmcnt(7)
	v_add_u32_e32 v17, v17, v7
	s_waitcnt vmcnt(6)
	v_add_u32_e32 v17, v17, v8
	s_waitcnt vmcnt(5)
	v_add_u32_e32 v17, v17, v9
	s_waitcnt vmcnt(4)
	v_add_u32_e32 v17, v17, v10
	s_waitcnt vmcnt(3)
	v_add_u32_e32 v17, v17, v11
	s_waitcnt vmcnt(2)
	v_add_u32_e32 v17, v17, v12
	s_waitcnt vmcnt(1)
	v_add_u32_e32 v17, v17, v13
	s_waitcnt vmcnt(0)
	v_add_u32_e32 v17, v17, v14
	v_cmp_eq_u32_e32 vcc, s26, v17
	s_cbranch_vccnz .LBB0_1827
	s_and_b32 s52, s58, 0xff
	s_cmp_eq_u32 s52, 0
	s_mov_b64 s[52:53], -1
	s_mov_b64 s[56:57], -1
	s_nop 0
	s_cbranch_scc0 .LBB0_1832
	global_load_dword v17, v16, s[2:3] sc1
	s_waitcnt vmcnt(0)
	v_cmp_eq_u32_e32 vcc, 0, v17
	s_cbranch_vccnz .LBB0_1834
	s_mov_b64 s[56:57], 0

; DI unsigned xb_ld(unsigned* p)              { return __hip_atomic_load(p, __ATOMIC_RELAXED, __HIP_MEMORY_SCOPE_AGENT); }
; DI void xcd_barrier_complete(unsigned* bar, unsigned x, unsigned& nloc, unsigned& nx) {
;     ...
;     for (;;) {
;         sum = 0u; cnt = 0u; mine = 0u;
; #pragma unroll
;         for (unsigned j = 0; j < 16; ++j) { const unsigned c = xb_ld(&bar[XB_XCNT(j)]); sum += c; cnt += (c > 0u) ? 1u : 0u; mine = (j == x) ? c : mine; }
;         if (sum == G) break;
;         __builtin_amdgcn_s_sleep(1);
;         if ((++sp & 255u) == 0u) { if (xb_ld(&bar[XB_TMO])) break; if (sp > XB_SPIN_CAP) { atomicAdd(&bar[XB_TMO], 1u); break; } }
;     }
.LBB0_1965:
	global_load_dword v15, v16, s[4:5] sc1
	global_load_dword v0, v16, s[6:7] sc1
	global_load_dword v1, v16, s[8:9] sc1
	global_load_dword v2, v16, s[10:11] sc1
	global_load_dword v3, v16, s[14:15] sc1
	global_load_dword v4, v16, s[34:35] sc1
	global_load_dword v5, v16, s[36:37] sc1
	global_load_dword v6, v16, s[38:39] sc1
	global_load_dword v7, v16, s[40:41] sc1
	global_load_dword v8, v16, s[42:43] sc1
	global_load_dword v9, v16, s[44:45] sc1
	global_load_dword v10, v16, s[46:47] sc1
	global_load_dword v11, v16, s[48:49] sc1
	global_load_dword v12, v16, s[50:51] sc1
	global_load_dword v13, v16, s[52:53] sc1
	global_load_dword v14, v16, s[54:55] sc1
	s_mov_b64 s[56:57], -1
	s_mov_b64 s[58:59], -1
	s_waitcnt vmcnt(14)
	v_add_u32_e32 v17, v0, v15
	s_waitcnt vmcnt(13)
	v_add_u32_e32 v17, v17, v1
	s_waitcnt vmcnt(12)
	v_add_u32_e32 v17, v17, v2
	s_waitcnt vmcnt(11)
	v_add_u32_e32 v17, v17, v3
	s_waitcnt vmcnt(10)
	v_add_u32_e32 v17, v17, v4
	s_waitcnt vmcnt(9)
	v_add_u32_e32 v17, v17, v5
	s_waitcnt vmcnt(8)
	v_add_u32_e32 v17, v17, v6
	s_waitcnt vmcnt(7)
	v_add_u32_e32 v17, v17, v7
	s_waitcnt vmcnt(6)
	v_add_u32_e32 v17, v17, v8
	s_waitcnt vmcnt(5)
	v_add_u32_e32 v17, v17, v9
	s_waitcnt vmcnt(4)
	v_add_u32_e32 v17, v17, v10
	s_waitcnt vmcnt(3)
	v_add_u32_e32 v17, v17, v11
	s_waitcnt vmcnt(2)
	v_add_u32_e32 v17, v17, v12
	s_waitcnt vmcnt(1)
	v_add_u32_e32 v17, v17, v13
	s_waitcnt vmcnt(0)
	v_add_u32_e32 v17, v17, v14
	v_cmp_eq_u32_e32 vcc, s71, v17
	s_cbranch_vccnz .LBB0_1964
	s_and_b32 s56, s74, 0xff
	s_cmp_eq_u32 s56, 0
	s_mov_b64 s[56:57], -1
	s_mov_b64 s[72:73], -1
	s_nop 0
	s_cbranch_scc0 .LBB0_1969
	global_load_dword v17, v16, s[2:3] sc1
	s_waitcnt vmcnt(0)
	v_cmp_eq_u32_e32 vcc, 0, v17
	s_cbranch_vccnz .LBB0_1971
	s_mov_b64 s[72:73], 0

; DI unsigned xb_ld(unsigned* p)              { return __hip_atomic_load(p, __ATOMIC_RELAXED, __HIP_MEMORY_SCOPE_AGENT); }
; DI unsigned xb_add(unsigned* p, unsigned v) { return __hip_atomic_fetch_add(p, v, __ATOMIC_RELAXED, __HIP_MEMORY_SCOPE_AGENT); }
; #define XB_SPIN(cond, bar) do { unsigned _sp = 0; while (cond) { __builtin_amdgcn_s_sleep(1); \
;     if ((++_sp & 255u) == 0u) { if (xb_ld(&(bar)[XB_TMO])) break; if (_sp > XB_SPIN_CAP) { atomicAdd(&(bar)[XB_TMO], 1u); break; } } } } while (0)
; DI void xcd_barrier(const XcdBarrier& b) {
;     ...
;             else XB_SPIN(xb_ld(&bar[XB_TOPGEN]) == tg, bar);
;             __builtin_amdgcn_fence(__ATOMIC_ACQUIRE, "agent");
;             xb_add(&bar[XB_XGEN(b.x)], 1u);
;             asm volatile("s_waitcnt vmcnt(0)" ::: "memory");
;         } else {
;             XB_SPIN(xb_ld(&bar[XB_XGEN(b.x)]) == gen, bar);
.LBB0_1983:
	s_and_b32 s38, s42, 0xff
	s_mov_b64 s[36:37], -1
	s_cmp_lg_u32 s38, 0
	s_mov_b64 s[40:41], -1
	s_nop 0
	s_cbranch_scc1 .LBB0_1986
	global_load_dword v2, v0, s[8:9] sc1
	s_waitcnt vmcnt(0)
	v_cmp_eq_u32_e32 vcc, 0, v2
	s_cbranch_vccnz .LBB0_1988
	s_mov_b64 s[40:41], 0
	s_mov_b64 s[38:39], -1

; DI unsigned xb_ld(unsigned* p)              { return __hip_atomic_load(p, __ATOMIC_RELAXED, __HIP_MEMORY_SCOPE_AGENT); }
; DI unsigned xb_add(unsigned* p, unsigned v) { return __hip_atomic_fetch_add(p, v, __ATOMIC_RELAXED, __HIP_MEMORY_SCOPE_AGENT); }
; #define XB_SPIN(cond, bar) do { unsigned _sp = 0; while (cond) { __builtin_amdgcn_s_sleep(1); \
;     if ((++_sp & 255u) == 0u) { if (xb_ld(&(bar)[XB_TMO])) break; if (_sp > XB_SPIN_CAP) { atomicAdd(&(bar)[XB_TMO], 1u); break; } } } } while (0)
; DI void xcd_barrier(const XcdBarrier& b) {
;     ...
;             else XB_SPIN(xb_ld(&bar[XB_TOPGEN]) == tg, bar);
;             __builtin_amdgcn_fence(__ATOMIC_ACQUIRE, "agent");
;             xb_add(&bar[XB_XGEN(b.x)], 1u);
;             asm volatile("s_waitcnt vmcnt(0)" ::: "memory");
;         } else {
;             XB_SPIN(xb_ld(&bar[XB_XGEN(b.x)]) == gen, bar);
.LBB0_2000:
	s_and_b32 s36, s42, 0xff
	s_cmp_lg_u32 s36, 0
	s_mov_b64 s[38:39], -1
	s_nop 0
	s_cbranch_scc1 .LBB0_2003
	global_load_dword v1, v0, s[8:9] sc1
	s_waitcnt vmcnt(0)
	v_cmp_eq_u32_e32 vcc, 0, v1
	s_cbranch_vccnz .LBB0_2005
	s_mov_b64 s[38:39], 0
	s_mov_b64 s[36:37], -1

; DI unsigned xb_ld(unsigned* p)              { return __hip_atomic_load(p, __ATOMIC_RELAXED, __HIP_MEMORY_SCOPE_AGENT); }
; DI void xcd_barrier_complete(unsigned* bar, unsigned x, unsigned& nloc, unsigned& nx) {
;     ...
;     for (;;) {
;         sum = 0u; cnt = 0u; mine = 0u;
; #pragma unroll
;         for (unsigned j = 0; j < 16; ++j) { const unsigned c = xb_ld(&bar[XB_XCNT(j)]); sum += c; cnt += (c > 0u) ? 1u : 0u; mine = (j == x) ? c : mine; }
;         if (sum == G) break;
;         __builtin_amdgcn_s_sleep(1);
;         if ((++sp & 255u) == 0u) { if (xb_ld(&bar[XB_TMO])) break; if (sp > XB_SPIN_CAP) { atomicAdd(&bar[XB_TMO], 1u); break; } }
;     }
.LBB0_2361:
	global_load_dword v15, v16, s[4:5] sc1
	global_load_dword v0, v16, s[6:7] sc1
	global_load_dword v1, v16, s[8:9] sc1
	global_load_dword v2, v16, s[10:11] sc1
	global_load_dword v3, v16, s[14:15] sc1
	global_load_dword v4, v16, s[36:37] sc1
	global_load_dword v5, v16, s[38:39] sc1
	global_load_dword v6, v16, s[40:41] sc1
	global_load_dword v7, v16, s[42:43] sc1
	global_load_dword v8, v16, s[44:45] sc1
	global_load_dword v9, v16, s[46:47] sc1
	global_load_dword v10, v16, s[48:49] sc1
	global_load_dword v11, v16, s[50:51] sc1
	global_load_dword v12, v16, s[52:53] sc1
	global_load_dword v13, v16, s[54:55] sc1
	global_load_dword v14, v16, s[56:57] sc1
	s_mov_b64 s[58:59], -1
	s_mov_b64 s[72:73], -1
	s_waitcnt vmcnt(14)
	v_add_u32_e32 v17, v0, v15
	s_waitcnt vmcnt(13)
	v_add_u32_e32 v17, v17, v1
	s_waitcnt vmcnt(12)
	v_add_u32_e32 v17, v17, v2
	s_waitcnt vmcnt(11)
	v_add_u32_e32 v17, v17, v3
	s_waitcnt vmcnt(10)
	v_add_u32_e32 v17, v17, v4
	s_waitcnt vmcnt(9)
	v_add_u32_e32 v17, v17, v5
	s_waitcnt vmcnt(8)
	v_add_u32_e32 v17, v17, v6
	s_waitcnt vmcnt(7)
	v_add_u32_e32 v17, v17, v7
	s_waitcnt vmcnt(6)
	v_add_u32_e32 v17, v17, v8
	s_waitcnt vmcnt(5)
	v_add_u32_e32 v17, v17, v9
	s_waitcnt vmcnt(4)
	v_add_u32_e32 v17, v17, v10
	s_waitcnt vmcnt(3)
	v_add_u32_e32 v17, v17, v11
	s_waitcnt vmcnt(2)
	v_add_u32_e32 v17, v17, v12
	s_waitcnt vmcnt(1)
	v_add_u32_e32 v17, v17, v13
	s_waitcnt vmcnt(0)
	v_add_u32_e32 v17, v17, v14
	v_cmp_eq_u32_e32 vcc, s71, v17
	s_cbranch_vccnz .LBB0_2360
	s_and_b32 s58, s76, 0xff
	s_cmp_eq_u32 s58, 0
	s_mov_b64 s[58:59], -1
	s_mov_b64 s[74:75], -1
	s_nop 0
	s_cbranch_scc0 .LBB0_2365
	global_load_dword v17, v16, s[2:3] sc1
	s_waitcnt vmcnt(0)
	v_cmp_eq_u32_e32 vcc, 0, v17
	s_cbranch_vccnz .LBB0_2367
	s_mov_b64 s[74:75], 0

; DI unsigned xb_ld(unsigned* p)              { return __hip_atomic_load(p, __ATOMIC_RELAXED, __HIP_MEMORY_SCOPE_AGENT); }
; DI unsigned xb_add(unsigned* p, unsigned v) { return __hip_atomic_fetch_add(p, v, __ATOMIC_RELAXED, __HIP_MEMORY_SCOPE_AGENT); }
; #define XB_SPIN(cond, bar) do { unsigned _sp = 0; while (cond) { __builtin_amdgcn_s_sleep(1); \
;     if ((++_sp & 255u) == 0u) { if (xb_ld(&(bar)[XB_TMO])) break; if (_sp > XB_SPIN_CAP) { atomicAdd(&(bar)[XB_TMO], 1u); break; } } } } while (0)
; DI void xcd_barrier(const XcdBarrier& b) {
;     ...
;             else XB_SPIN(xb_ld(&bar[XB_TOPGEN]) == tg, bar);
;             __builtin_amdgcn_fence(__ATOMIC_ACQUIRE, "agent");
;             xb_add(&bar[XB_XGEN(b.x)], 1u);
;             asm volatile("s_waitcnt vmcnt(0)" ::: "memory");
;         } else {
;             XB_SPIN(xb_ld(&bar[XB_XGEN(b.x)]) == gen, bar);
.LBB0_2379:
	s_and_b32 s40, s44, 0xff
	s_mov_b64 s[38:39], -1
	s_cmp_lg_u32 s40, 0
	s_mov_b64 s[42:43], -1
	s_nop 0
	s_cbranch_scc1 .LBB0_2382
	global_load_dword v2, v0, s[8:9] sc1
	s_waitcnt vmcnt(0)
	v_cmp_eq_u32_e32 vcc, 0, v2
	s_cbranch_vccnz .LBB0_2384
	s_mov_b64 s[42:43], 0
	s_mov_b64 s[40:41], -1

; DI unsigned xb_ld(unsigned* p)              { return __hip_atomic_load(p, __ATOMIC_RELAXED, __HIP_MEMORY_SCOPE_AGENT); }
; DI unsigned xb_add(unsigned* p, unsigned v) { return __hip_atomic_fetch_add(p, v, __ATOMIC_RELAXED, __HIP_MEMORY_SCOPE_AGENT); }
; #define XB_SPIN(cond, bar) do { unsigned _sp = 0; while (cond) { __builtin_amdgcn_s_sleep(1); \
;     if ((++_sp & 255u) == 0u) { if (xb_ld(&(bar)[XB_TMO])) break; if (_sp > XB_SPIN_CAP) { atomicAdd(&(bar)[XB_TMO], 1u); break; } } } } while (0)
; DI void xcd_barrier(const XcdBarrier& b) {
;     ...
;             else XB_SPIN(xb_ld(&bar[XB_TOPGEN]) == tg, bar);
;             __builtin_amdgcn_fence(__ATOMIC_ACQUIRE, "agent");
;             xb_add(&bar[XB_XGEN(b.x)], 1u);
;             asm volatile("s_waitcnt vmcnt(0)" ::: "memory");
;         } else {
;             XB_SPIN(xb_ld(&bar[XB_XGEN(b.x)]) == gen, bar);
.LBB0_2396:
	s_and_b32 s38, s44, 0xff
	s_cmp_lg_u32 s38, 0
	s_mov_b64 s[40:41], -1
	s_nop 0
	s_cbranch_scc1 .LBB0_2399
	global_load_dword v1, v0, s[8:9] sc1
	s_waitcnt vmcnt(0)
	v_cmp_eq_u32_e32 vcc, 0, v1
	s_cbranch_vccnz .LBB0_2401
	s_mov_b64 s[40:41], 0
	s_mov_b64 s[38:39], -1

; DI unsigned xb_ld(unsigned* p)              { return __hip_atomic_load(p, __ATOMIC_RELAXED, __HIP_MEMORY_SCOPE_AGENT); }
; DI void xcd_barrier_complete(unsigned* bar, unsigned x, unsigned& nloc, unsigned& nx) {
;     ...
;     for (;;) {
;         sum = 0u; cnt = 0u; mine = 0u;
; #pragma unroll
;         for (unsigned j = 0; j < 16; ++j) { const unsigned c = xb_ld(&bar[XB_XCNT(j)]); sum += c; cnt += (c > 0u) ? 1u : 0u; mine = (j == x) ? c : mine; }
;         if (sum == G) break;
;         __builtin_amdgcn_s_sleep(1);
;         if ((++sp & 255u) == 0u) { if (xb_ld(&bar[XB_TMO])) break; if (sp > XB_SPIN_CAP) { atomicAdd(&bar[XB_TMO], 1u); break; } }
;     }
.LBB0_2447:
	global_load_dword v15, v16, s[4:5] sc1
	global_load_dword v0, v16, s[6:7] sc1
	global_load_dword v1, v16, s[8:9] sc1
	global_load_dword v2, v16, s[10:11] sc1
	global_load_dword v3, v16, s[12:13] sc1
	global_load_dword v4, v16, s[14:15] sc1
	global_load_dword v5, v16, s[34:35] sc1
	global_load_dword v6, v16, s[36:37] sc1
	global_load_dword v7, v16, s[38:39] sc1
	global_load_dword v8, v16, s[40:41] sc1
	global_load_dword v9, v16, s[42:43] sc1
	global_load_dword v10, v16, s[44:45] sc1
	global_load_dword v11, v16, s[46:47] sc1
	global_load_dword v12, v16, s[48:49] sc1
	global_load_dword v13, v16, s[50:51] sc1
	global_load_dword v14, v16, s[52:53] sc1
	s_mov_b64 s[54:55], -1
	s_mov_b64 s[56:57], -1
	s_waitcnt vmcnt(14)
	v_add_u32_e32 v17, v0, v15
	s_waitcnt vmcnt(13)
	v_add_u32_e32 v17, v17, v1
	s_waitcnt vmcnt(12)
	v_add_u32_e32 v17, v17, v2
	s_waitcnt vmcnt(11)
	v_add_u32_e32 v17, v17, v3
	s_waitcnt vmcnt(10)
	v_add_u32_e32 v17, v17, v4
	s_waitcnt vmcnt(9)
	v_add_u32_e32 v17, v17, v5
	s_waitcnt vmcnt(8)
	v_add_u32_e32 v17, v17, v6
	s_waitcnt vmcnt(7)
	v_add_u32_e32 v17, v17, v7
	s_waitcnt vmcnt(6)
	v_add_u32_e32 v17, v17, v8
	s_waitcnt vmcnt(5)
	v_add_u32_e32 v17, v17, v9
	s_waitcnt vmcnt(4)
	v_add_u32_e32 v17, v17, v10
	s_waitcnt vmcnt(3)
	v_add_u32_e32 v17, v17, v11
	s_waitcnt vmcnt(2)
	v_add_u32_e32 v17, v17, v12
	s_waitcnt vmcnt(1)
	v_add_u32_e32 v17, v17, v13
	s_waitcnt vmcnt(0)
	v_add_u32_e32 v17, v17, v14
	v_cmp_eq_u32_e32 vcc, s31, v17
	s_cbranch_vccnz .LBB0_2446
	s_and_b32 s54, s71, 0xff
	s_cmp_eq_u32 s54, 0
	s_mov_b64 s[54:55], -1
	s_mov_b64 s[58:59], -1
	s_nop 0
	s_cbranch_scc0 .LBB0_2451
	global_load_dword v17, v16, s[2:3] sc1
	s_waitcnt vmcnt(0)
	v_cmp_eq_u32_e32 vcc, 0, v17
	s_cbranch_vccnz .LBB0_2453
	s_mov_b64 s[58:59], 0

; DI unsigned xb_ld(unsigned* p)              { return __hip_atomic_load(p, __ATOMIC_RELAXED, __HIP_MEMORY_SCOPE_AGENT); }
; DI unsigned xb_add(unsigned* p, unsigned v) { return __hip_atomic_fetch_add(p, v, __ATOMIC_RELAXED, __HIP_MEMORY_SCOPE_AGENT); }
; #define XB_SPIN(cond, bar) do { unsigned _sp = 0; while (cond) { __builtin_amdgcn_s_sleep(1); \
;     if ((++_sp & 255u) == 0u) { if (xb_ld(&(bar)[XB_TMO])) break; if (_sp > XB_SPIN_CAP) { atomicAdd(&(bar)[XB_TMO], 1u); break; } } } } while (0)
; DI void xcd_barrier(const XcdBarrier& b) {
;     ...
;             else XB_SPIN(xb_ld(&bar[XB_TOPGEN]) == tg, bar);
;             __builtin_amdgcn_fence(__ATOMIC_ACQUIRE, "agent");
;             xb_add(&bar[XB_XGEN(b.x)], 1u);
;             asm volatile("s_waitcnt vmcnt(0)" ::: "memory");
;         } else {
;             XB_SPIN(xb_ld(&bar[XB_XGEN(b.x)]) == gen, bar);
.LBB0_2465:
	s_and_b32 s36, s31, 0xff
	s_mov_b64 s[34:35], -1
	s_cmp_lg_u32 s36, 0
	s_mov_b64 s[38:39], -1
	s_nop 0
	s_cbranch_scc1 .LBB0_2468
	global_load_dword v2, v0, s[8:9] sc1
	s_waitcnt vmcnt(0)
	v_cmp_eq_u32_e32 vcc, 0, v2
	s_cbranch_vccnz .LBB0_2470
	s_mov_b64 s[38:39], 0
	s_mov_b64 s[36:37], -1

; DI unsigned xb_ld(unsigned* p)              { return __hip_atomic_load(p, __ATOMIC_RELAXED, __HIP_MEMORY_SCOPE_AGENT); }
; DI unsigned xb_add(unsigned* p, unsigned v) { return __hip_atomic_fetch_add(p, v, __ATOMIC_RELAXED, __HIP_MEMORY_SCOPE_AGENT); }
; #define XB_SPIN(cond, bar) do { unsigned _sp = 0; while (cond) { __builtin_amdgcn_s_sleep(1); \
;     if ((++_sp & 255u) == 0u) { if (xb_ld(&(bar)[XB_TMO])) break; if (_sp > XB_SPIN_CAP) { atomicAdd(&(bar)[XB_TMO], 1u); break; } } } } while (0)
; DI void xcd_barrier(const XcdBarrier& b) {
;     ...
;             else XB_SPIN(xb_ld(&bar[XB_TOPGEN]) == tg, bar);
;             __builtin_amdgcn_fence(__ATOMIC_ACQUIRE, "agent");
;             xb_add(&bar[XB_XGEN(b.x)], 1u);
;             asm volatile("s_waitcnt vmcnt(0)" ::: "memory");
;         } else {
;             XB_SPIN(xb_ld(&bar[XB_XGEN(b.x)]) == gen, bar);
.LBB0_2482:
	s_and_b32 s34, s31, 0xff
	s_cmp_lg_u32 s34, 0
	s_mov_b64 s[36:37], -1
	s_nop 0
	s_cbranch_scc1 .LBB0_2485
	global_load_dword v1, v0, s[8:9] sc1
	s_waitcnt vmcnt(0)
	v_cmp_eq_u32_e32 vcc, 0, v1
	s_cbranch_vccnz .LBB0_2487
	s_mov_b64 s[36:37], 0
	s_mov_b64 s[34:35], -1

; DI unsigned xb_ld(unsigned* p)              { return __hip_atomic_load(p, __ATOMIC_RELAXED, __HIP_MEMORY_SCOPE_AGENT); }
; DI void xcd_barrier_complete(unsigned* bar, unsigned x, unsigned& nloc, unsigned& nx) {
;     ...
;     for (;;) {
;         sum = 0u; cnt = 0u; mine = 0u;
; #pragma unroll
;         for (unsigned j = 0; j < 16; ++j) { const unsigned c = xb_ld(&bar[XB_XCNT(j)]); sum += c; cnt += (c > 0u) ? 1u : 0u; mine = (j == x) ? c : mine; }
;         if (sum == G) break;
;         __builtin_amdgcn_s_sleep(1);
;         if ((++sp & 255u) == 0u) { if (xb_ld(&bar[XB_TMO])) break; if (sp > XB_SPIN_CAP) { atomicAdd(&bar[XB_TMO], 1u); break; } }
;     }
.LBB0_3154:
	global_load_dword v15, v16, s[4:5] sc1
	global_load_dword v0, v16, s[8:9] sc1
	global_load_dword v1, v16, s[10:11] sc1
	global_load_dword v2, v16, s[12:13] sc1
	global_load_dword v3, v16, s[14:15] sc1
	global_load_dword v4, v16, s[24:25] sc1
	global_load_dword v5, v16, s[30:31] sc1
	global_load_dword v6, v16, s[34:35] sc1
	global_load_dword v7, v16, s[36:37] sc1
	global_load_dword v8, v16, s[38:39] sc1
	global_load_dword v9, v16, s[40:41] sc1
	global_load_dword v10, v16, s[42:43] sc1
	global_load_dword v11, v16, s[44:45] sc1
	global_load_dword v12, v16, s[46:47] sc1
	global_load_dword v13, v16, s[48:49] sc1
	global_load_dword v14, v16, s[50:51] sc1
	s_mov_b64 s[52:53], -1
	s_mov_b64 s[54:55], -1
	s_waitcnt vmcnt(14)
	v_add_u32_e32 v17, v0, v15
	s_waitcnt vmcnt(13)
	v_add_u32_e32 v17, v17, v1
	s_waitcnt vmcnt(12)
	v_add_u32_e32 v17, v17, v2
	s_waitcnt vmcnt(11)
	v_add_u32_e32 v17, v17, v3
	s_waitcnt vmcnt(10)
	v_add_u32_e32 v17, v17, v4
	s_waitcnt vmcnt(9)
	v_add_u32_e32 v17, v17, v5
	s_waitcnt vmcnt(8)
	v_add_u32_e32 v17, v17, v6
	s_waitcnt vmcnt(7)
	v_add_u32_e32 v17, v17, v7
	s_waitcnt vmcnt(6)
	v_add_u32_e32 v17, v17, v8
	s_waitcnt vmcnt(5)
	v_add_u32_e32 v17, v17, v9
	s_waitcnt vmcnt(4)
	v_add_u32_e32 v17, v17, v10
	s_waitcnt vmcnt(3)
	v_add_u32_e32 v17, v17, v11
	s_waitcnt vmcnt(2)
	v_add_u32_e32 v17, v17, v12
	s_waitcnt vmcnt(1)
	v_add_u32_e32 v17, v17, v13
	s_waitcnt vmcnt(0)
	v_add_u32_e32 v17, v17, v14
	v_cmp_eq_u32_e32 vcc, s58, v17
	s_cbranch_vccnz .LBB0_3153
	s_and_b32 s52, s59, 0xff
	s_cmp_eq_u32 s52, 0
	s_mov_b64 s[52:53], -1
	s_mov_b64 s[56:57], -1
	s_nop 0
	s_cbranch_scc0 .LBB0_3158
	global_load_dword v17, v16, s[2:3] sc1
	s_waitcnt vmcnt(0)
	v_cmp_eq_u32_e32 vcc, 0, v17
	s_cbranch_vccnz .LBB0_3160
	s_mov_b64 s[56:57], 0

; DI unsigned xb_ld(unsigned* p)              { return __hip_atomic_load(p, __ATOMIC_RELAXED, __HIP_MEMORY_SCOPE_AGENT); }
; DI void xcd_barrier_complete(unsigned* bar, unsigned x, unsigned& nloc, unsigned& nx) {
;     ...
;     for (;;) {
;         sum = 0u; cnt = 0u; mine = 0u;
; #pragma unroll
;         for (unsigned j = 0; j < 16; ++j) { const unsigned c = xb_ld(&bar[XB_XCNT(j)]); sum += c; cnt += (c > 0u) ? 1u : 0u; mine = (j == x) ? c : mine; }
;         if (sum == G) break;
;         __builtin_amdgcn_s_sleep(1);
;         if ((++sp & 255u) == 0u) { if (xb_ld(&bar[XB_TMO])) break; if (sp > XB_SPIN_CAP) { atomicAdd(&bar[XB_TMO], 1u); break; } }
;     }
.LBB0_3339:
	global_load_dword v15, v16, s[4:5] sc1
	global_load_dword v0, v16, s[10:11] sc1
	global_load_dword v1, v16, s[12:13] sc1
	global_load_dword v2, v16, s[14:15] sc1
	global_load_dword v3, v16, s[24:25] sc1
	global_load_dword v4, v16, s[30:31] sc1
	global_load_dword v5, v16, s[34:35] sc1
	global_load_dword v6, v16, s[36:37] sc1
	global_load_dword v7, v16, s[38:39] sc1
	global_load_dword v8, v16, s[40:41] sc1
	global_load_dword v9, v16, s[42:43] sc1
	global_load_dword v10, v16, s[44:45] sc1
	global_load_dword v11, v16, s[46:47] sc1
	global_load_dword v12, v16, s[48:49] sc1
	global_load_dword v13, v16, s[50:51] sc1
	global_load_dword v14, v16, s[52:53] sc1
	s_mov_b64 s[54:55], -1
	s_mov_b64 s[56:57], -1
	s_waitcnt vmcnt(14)
	v_add_u32_e32 v17, v0, v15
	s_waitcnt vmcnt(13)
	v_add_u32_e32 v17, v17, v1
	s_waitcnt vmcnt(12)
	v_add_u32_e32 v17, v17, v2
	s_waitcnt vmcnt(11)
	v_add_u32_e32 v17, v17, v3
	s_waitcnt vmcnt(10)
	v_add_u32_e32 v17, v17, v4
	s_waitcnt vmcnt(9)
	v_add_u32_e32 v17, v17, v5
	s_waitcnt vmcnt(8)
	v_add_u32_e32 v17, v17, v6
	s_waitcnt vmcnt(7)
	v_add_u32_e32 v17, v17, v7
	s_waitcnt vmcnt(6)
	v_add_u32_e32 v17, v17, v8
	s_waitcnt vmcnt(5)
	v_add_u32_e32 v17, v17, v9
	s_waitcnt vmcnt(4)
	v_add_u32_e32 v17, v17, v10
	s_waitcnt vmcnt(3)
	v_add_u32_e32 v17, v17, v11
	s_waitcnt vmcnt(2)
	v_add_u32_e32 v17, v17, v12
	s_waitcnt vmcnt(1)
	v_add_u32_e32 v17, v17, v13
	s_waitcnt vmcnt(0)
	v_add_u32_e32 v17, v17, v14
	v_cmp_eq_u32_e32 vcc, s63, v17
	s_cbranch_vccnz .LBB0_3338
	s_and_b32 s54, s64, 0xff
	s_cmp_eq_u32 s54, 0
	s_mov_b64 s[54:55], -1
	s_mov_b64 s[58:59], -1
	s_nop 0
	s_cbranch_scc0 .LBB0_3343
	global_load_dword v17, v16, s[2:3] sc1
	s_waitcnt vmcnt(0)
	v_cmp_eq_u32_e32 vcc, 0, v17
	s_cbranch_vccnz .LBB0_3345
	s_mov_b64 s[58:59], 0

; DI unsigned xb_ld(unsigned* p)              { return __hip_atomic_load(p, __ATOMIC_RELAXED, __HIP_MEMORY_SCOPE_AGENT); }
; DI void xcd_barrier_complete(unsigned* bar, unsigned x, unsigned& nloc, unsigned& nx) {
;     const unsigned G = gridDim.x * gridDim.y * gridDim.z;
;     unsigned sum, cnt, mine, sp = 0u;
;     for (;;) {
;         sum = 0u; cnt = 0u; mine = 0u;
; #pragma unroll
;         for (unsigned j = 0; j < 16; ++j) { const unsigned c = xb_ld(&bar[XB_XCNT(j)]); sum += c; cnt += (c > 0u) ? 1u : 0u; mine = (j == x) ? c : mine; }
;         if (sum == G) break;
;         __builtin_amdgcn_s_sleep(1);
;         if ((++sp & 255u) == 0u) { if (xb_ld(&bar[XB_TMO])) break; if (sp > XB_SPIN_CAP) { atomicAdd(&bar[XB_TMO], 1u); break; } }
;     }
;     nloc = mine > 0u ? mine : 1u; nx = cnt > 0u ? cnt : 1u;
; }
.LBB0_3401:
	global_load_dword v15, v16, s[4:5] sc1
	global_load_dword v0, v16, s[6:7] sc1
	global_load_dword v1, v16, s[8:9] sc1
	global_load_dword v2, v16, s[10:11] sc1
	global_load_dword v3, v16, s[12:13] sc1
	global_load_dword v4, v16, s[14:15] sc1
	global_load_dword v5, v16, s[24:25] sc1
	global_load_dword v6, v16, s[30:31] sc1
	global_load_dword v7, v16, s[34:35] sc1
	global_load_dword v8, v16, s[36:37] sc1
	global_load_dword v9, v16, s[38:39] sc1
	global_load_dword v10, v16, s[40:41] sc1
	global_load_dword v11, v16, s[42:43] sc1
	global_load_dword v12, v16, s[44:45] sc1
	global_load_dword v13, v16, s[46:47] sc1
	global_load_dword v14, v16, s[48:49] sc1
	s_mov_b64 s[50:51], -1
	s_mov_b64 s[52:53], -1
	s_waitcnt vmcnt(14)
	v_add_u32_e32 v17, v0, v15
	s_waitcnt vmcnt(13)
	v_add_u32_e32 v17, v17, v1
	s_waitcnt vmcnt(12)
	v_add_u32_e32 v17, v17, v2
	s_waitcnt vmcnt(11)
	v_add_u32_e32 v17, v17, v3
	s_waitcnt vmcnt(10)
	v_add_u32_e32 v17, v17, v4
	s_waitcnt vmcnt(9)
	v_add_u32_e32 v17, v17, v5
	s_waitcnt vmcnt(8)
	v_add_u32_e32 v17, v17, v6
	s_waitcnt vmcnt(7)
	v_add_u32_e32 v17, v17, v7
	s_waitcnt vmcnt(6)
	v_add_u32_e32 v17, v17, v8
	s_waitcnt vmcnt(5)
	v_add_u32_e32 v17, v17, v9
	s_waitcnt vmcnt(4)
	v_add_u32_e32 v17, v17, v10
	s_waitcnt vmcnt(3)
	v_add_u32_e32 v17, v17, v11
	s_waitcnt vmcnt(2)
	v_add_u32_e32 v17, v17, v12
	s_waitcnt vmcnt(1)
	v_add_u32_e32 v17, v17, v13
	s_waitcnt vmcnt(0)
	v_add_u32_e32 v17, v17, v14
	v_cmp_eq_u32_e32 vcc, s56, v17
	s_cbranch_vccnz .LBB0_3400
	s_and_b32 s50, s57, 0xff
	s_cmp_eq_u32 s50, 0
	s_mov_b64 s[50:51], -1
	s_mov_b64 s[54:55], -1
	s_nop 0
	s_cbranch_scc0 .LBB0_3405
	global_load_dword v17, v16, s[2:3] sc1
	s_waitcnt vmcnt(0)
	v_cmp_eq_u32_e32 vcc, 0, v17
	s_cbranch_vccnz .LBB0_3407
	s_mov_b64 s[54:55], 0

; DI unsigned xb_ld(unsigned* p)              { return __hip_atomic_load(p, __ATOMIC_RELAXED, __HIP_MEMORY_SCOPE_AGENT); }
; DI unsigned xb_add(unsigned* p, unsigned v) { return __hip_atomic_fetch_add(p, v, __ATOMIC_RELAXED, __HIP_MEMORY_SCOPE_AGENT); }
; #define XB_SPIN(cond, bar) do { unsigned _sp = 0; while (cond) { __builtin_amdgcn_s_sleep(1); \
;     if ((++_sp & 255u) == 0u) { if (xb_ld(&(bar)[XB_TMO])) break; if (_sp > XB_SPIN_CAP) { atomicAdd(&(bar)[XB_TMO], 1u); break; } } } } while (0)
; DI void xcd_barrier(const XcdBarrier& b) {
;     ...
;             const unsigned og = xb_add(&bar[XB_TOP], 1u);
;             const unsigned tg = og / nx;
;             if (og + 1u == (tg + 1u) * nx) xb_add(&bar[XB_TOPGEN], 1u);
;             else XB_SPIN(xb_ld(&bar[XB_TOPGEN]) == tg, bar);
;             __builtin_amdgcn_fence(__ATOMIC_ACQUIRE, "agent");
;             xb_add(&bar[XB_XGEN(b.x)], 1u);
;             asm volatile("s_waitcnt vmcnt(0)" ::: "memory");
;         } else {
;             XB_SPIN(xb_ld(&bar[XB_XGEN(b.x)]) == gen, bar);
;             __builtin_amdgcn_fence(__ATOMIC_ACQUIRE, "agent");
;             asm volatile("s_waitcnt vmcnt(0)" ::: "memory");
.LBB0_3419:
	s_and_b32 s30, s36, 0xff
	s_mov_b64 s[24:25], -1
	s_cmp_lg_u32 s30, 0
	s_mov_b64 s[34:35], -1
	s_nop 0
	s_cbranch_scc1 .LBB0_3422
	global_load_dword v2, v0, s[8:9] sc1
	s_waitcnt vmcnt(0)
	v_cmp_eq_u32_e32 vcc, 0, v2
	s_cbranch_vccnz .LBB0_3424
	s_mov_b64 s[34:35], 0
	s_mov_b64 s[30:31], -1

; DI unsigned xb_ld(unsigned* p)              { return __hip_atomic_load(p, __ATOMIC_RELAXED, __HIP_MEMORY_SCOPE_AGENT); }
; DI unsigned xb_add(unsigned* p, unsigned v) { return __hip_atomic_fetch_add(p, v, __ATOMIC_RELAXED, __HIP_MEMORY_SCOPE_AGENT); }
; #define XB_SPIN(cond, bar) do { unsigned _sp = 0; while (cond) { __builtin_amdgcn_s_sleep(1); \
;     if ((++_sp & 255u) == 0u) { if (xb_ld(&(bar)[XB_TMO])) break; if (_sp > XB_SPIN_CAP) { atomicAdd(&(bar)[XB_TMO], 1u); break; } } } } while (0)
; DI void xcd_barrier(const XcdBarrier& b) {
;     ...
;             const unsigned og = xb_add(&bar[XB_TOP], 1u);
;             const unsigned tg = og / nx;
;             if (og + 1u == (tg + 1u) * nx) xb_add(&bar[XB_TOPGEN], 1u);
;             else XB_SPIN(xb_ld(&bar[XB_TOPGEN]) == tg, bar);
;             __builtin_amdgcn_fence(__ATOMIC_ACQUIRE, "agent");
;             xb_add(&bar[XB_XGEN(b.x)], 1u);
;             asm volatile("s_waitcnt vmcnt(0)" ::: "memory");
;         } else {
;             XB_SPIN(xb_ld(&bar[XB_XGEN(b.x)]) == gen, bar);
;             __builtin_amdgcn_fence(__ATOMIC_ACQUIRE, "agent");
;             asm volatile("s_waitcnt vmcnt(0)" ::: "memory");
.LBB0_3436:
	s_and_b32 s24, s36, 0xff
	s_cmp_lg_u32 s24, 0
	s_mov_b64 s[30:31], -1
	s_nop 0
	s_cbranch_scc1 .LBB0_3439
	global_load_dword v1, v0, s[8:9] sc1
	s_waitcnt vmcnt(0)
	v_cmp_eq_u32_e32 vcc, 0, v1
	s_cbranch_vccnz .LBB0_3441
	s_mov_b64 s[30:31], 0
	s_mov_b64 s[24:25], -1

; DI unsigned xb_ld(unsigned* p)              { return __hip_atomic_load(p, __ATOMIC_RELAXED, __HIP_MEMORY_SCOPE_AGENT); }
; DI void xcd_barrier_complete(unsigned* bar, unsigned x, unsigned& nloc, unsigned& nx) {
;     const unsigned G = gridDim.x * gridDim.y * gridDim.z;
;     unsigned sum, cnt, mine, sp = 0u;
;     for (;;) {
;         sum = 0u; cnt = 0u; mine = 0u;
; #pragma unroll
;         for (unsigned j = 0; j < 16; ++j) { const unsigned c = xb_ld(&bar[XB_XCNT(j)]); sum += c; cnt += (c > 0u) ? 1u : 0u; mine = (j == x) ? c : mine; }
;         if (sum == G) break;
;         __builtin_amdgcn_s_sleep(1);
;         if ((++sp & 255u) == 0u) { if (xb_ld(&bar[XB_TMO])) break; if (sp > XB_SPIN_CAP) { atomicAdd(&bar[XB_TMO], 1u); break; } }
;     }
;     nloc = mine > 0u ? mine : 1u; nx = cnt > 0u ? cnt : 1u;
; }
.LBB0_3513:
	global_load_dword v15, v16, s[4:5] sc1
	global_load_dword v0, v16, s[6:7] sc1
	global_load_dword v1, v16, s[8:9] sc1
	global_load_dword v2, v16, s[10:11] sc1
	global_load_dword v3, v16, s[12:13] sc1
	global_load_dword v4, v16, s[14:15] sc1
	global_load_dword v5, v16, s[22:23] sc1
	global_load_dword v6, v16, s[24:25] sc1
	global_load_dword v7, v16, s[30:31] sc1
	global_load_dword v8, v16, s[34:35] sc1
	global_load_dword v9, v16, s[36:37] sc1
	global_load_dword v10, v16, s[38:39] sc1
	global_load_dword v11, v16, s[40:41] sc1
	global_load_dword v12, v16, s[42:43] sc1
	global_load_dword v13, v16, s[44:45] sc1
	global_load_dword v14, v16, s[46:47] sc1
	s_mov_b64 s[48:49], -1
	s_mov_b64 s[50:51], -1
	s_waitcnt vmcnt(14)
	v_add_u32_e32 v17, v0, v15
	s_waitcnt vmcnt(13)
	v_add_u32_e32 v17, v17, v1
	s_waitcnt vmcnt(12)
	v_add_u32_e32 v17, v17, v2
	s_waitcnt vmcnt(11)
	v_add_u32_e32 v17, v17, v3
	s_waitcnt vmcnt(10)
	v_add_u32_e32 v17, v17, v4
	s_waitcnt vmcnt(9)
	v_add_u32_e32 v17, v17, v5
	s_waitcnt vmcnt(8)
	v_add_u32_e32 v17, v17, v6
	s_waitcnt vmcnt(7)
	v_add_u32_e32 v17, v17, v7
	s_waitcnt vmcnt(6)
	v_add_u32_e32 v17, v17, v8
	s_waitcnt vmcnt(5)
	v_add_u32_e32 v17, v17, v9
	s_waitcnt vmcnt(4)
	v_add_u32_e32 v17, v17, v10
	s_waitcnt vmcnt(3)
	v_add_u32_e32 v17, v17, v11
	s_waitcnt vmcnt(2)
	v_add_u32_e32 v17, v17, v12
	s_waitcnt vmcnt(1)
	v_add_u32_e32 v17, v17, v13
	s_waitcnt vmcnt(0)
	v_add_u32_e32 v17, v17, v14
	v_cmp_eq_u32_e32 vcc, s54, v17
	s_cbranch_vccnz .LBB0_3512
	s_and_b32 s48, s55, 0xff
	s_cmp_eq_u32 s48, 0
	s_mov_b64 s[48:49], -1
	s_mov_b64 s[52:53], -1
	s_nop 0
	s_cbranch_scc0 .LBB0_3517
	global_load_dword v17, v16, s[2:3] sc1
	s_waitcnt vmcnt(0)
	v_cmp_eq_u32_e32 vcc, 0, v17
	s_cbranch_vccnz .LBB0_3519
	s_mov_b64 s[52:53], 0

; DI unsigned xb_ld(unsigned* p)              { return __hip_atomic_load(p, __ATOMIC_RELAXED, __HIP_MEMORY_SCOPE_AGENT); }
; DI unsigned xb_add(unsigned* p, unsigned v) { return __hip_atomic_fetch_add(p, v, __ATOMIC_RELAXED, __HIP_MEMORY_SCOPE_AGENT); }
; #define XB_SPIN(cond, bar) do { unsigned _sp = 0; while (cond) { __builtin_amdgcn_s_sleep(1); \
;     if ((++_sp & 255u) == 0u) { if (xb_ld(&(bar)[XB_TMO])) break; if (_sp > XB_SPIN_CAP) { atomicAdd(&(bar)[XB_TMO], 1u); break; } } } } while (0)
; DI void xcd_barrier(const XcdBarrier& b) {
;     ...
;             const unsigned og = xb_add(&bar[XB_TOP], 1u);
;             const unsigned tg = og / nx;
;             if (og + 1u == (tg + 1u) * nx) xb_add(&bar[XB_TOPGEN], 1u);
;             else XB_SPIN(xb_ld(&bar[XB_TOPGEN]) == tg, bar);
;             __builtin_amdgcn_fence(__ATOMIC_ACQUIRE, "agent");
;             xb_add(&bar[XB_XGEN(b.x)], 1u);
;             asm volatile("s_waitcnt vmcnt(0)" ::: "memory");
;         } else {
;             XB_SPIN(xb_ld(&bar[XB_XGEN(b.x)]) == gen, bar);
;             __builtin_amdgcn_fence(__ATOMIC_ACQUIRE, "agent");
;             asm volatile("s_waitcnt vmcnt(0)" ::: "memory");
.LBB0_3531:
	s_and_b32 s24, s34, 0xff
	s_mov_b64 s[22:23], -1
	s_cmp_lg_u32 s24, 0
	s_mov_b64 s[30:31], -1
	s_nop 0
	s_cbranch_scc1 .LBB0_3534
	global_load_dword v2, v0, s[8:9] sc1
	s_waitcnt vmcnt(0)
	v_cmp_eq_u32_e32 vcc, 0, v2
	s_cbranch_vccnz .LBB0_3536
	s_mov_b64 s[30:31], 0
	s_mov_b64 s[24:25], -1

; DI unsigned xb_ld(unsigned* p)              { return __hip_atomic_load(p, __ATOMIC_RELAXED, __HIP_MEMORY_SCOPE_AGENT); }
; DI unsigned xb_add(unsigned* p, unsigned v) { return __hip_atomic_fetch_add(p, v, __ATOMIC_RELAXED, __HIP_MEMORY_SCOPE_AGENT); }
; #define XB_SPIN(cond, bar) do { unsigned _sp = 0; while (cond) { __builtin_amdgcn_s_sleep(1); \
;     if ((++_sp & 255u) == 0u) { if (xb_ld(&(bar)[XB_TMO])) break; if (_sp > XB_SPIN_CAP) { atomicAdd(&(bar)[XB_TMO], 1u); break; } } } } while (0)
; DI void xcd_barrier(const XcdBarrier& b) {
;     ...
;             const unsigned og = xb_add(&bar[XB_TOP], 1u);
;             const unsigned tg = og / nx;
;             if (og + 1u == (tg + 1u) * nx) xb_add(&bar[XB_TOPGEN], 1u);
;             else XB_SPIN(xb_ld(&bar[XB_TOPGEN]) == tg, bar);
;             __builtin_amdgcn_fence(__ATOMIC_ACQUIRE, "agent");
;             xb_add(&bar[XB_XGEN(b.x)], 1u);
;             asm volatile("s_waitcnt vmcnt(0)" ::: "memory");
;         } else {
;             XB_SPIN(xb_ld(&bar[XB_XGEN(b.x)]) == gen, bar);
;             __builtin_amdgcn_fence(__ATOMIC_ACQUIRE, "agent");
;             asm volatile("s_waitcnt vmcnt(0)" ::: "memory");
.LBB0_3548:
	s_and_b32 s22, s34, 0xff
	s_cmp_lg_u32 s22, 0
	s_mov_b64 s[24:25], -1
	s_nop 0
	s_cbranch_scc1 .LBB0_3551
	global_load_dword v1, v0, s[8:9] sc1
	s_waitcnt vmcnt(0)
	v_cmp_eq_u32_e32 vcc, 0, v1
	s_cbranch_vccnz .LBB0_3553
	s_mov_b64 s[24:25], 0
	s_mov_b64 s[22:23], -1

; DI unsigned xb_ld(unsigned* p)              { return __hip_atomic_load(p, __ATOMIC_RELAXED, __HIP_MEMORY_SCOPE_AGENT); }
; DI void xcd_barrier_complete(unsigned* bar, unsigned x, unsigned& nloc, unsigned& nx) {
;     const unsigned G = gridDim.x * gridDim.y * gridDim.z;
;     unsigned sum, cnt, mine, sp = 0u;
;     for (;;) {
;         sum = 0u; cnt = 0u; mine = 0u;
; #pragma unroll
;         for (unsigned j = 0; j < 16; ++j) { const unsigned c = xb_ld(&bar[XB_XCNT(j)]); sum += c; cnt += (c > 0u) ? 1u : 0u; mine = (j == x) ? c : mine; }
;         if (sum == G) break;
;         __builtin_amdgcn_s_sleep(1);
;         if ((++sp & 255u) == 0u) { if (xb_ld(&bar[XB_TMO])) break; if (sp > XB_SPIN_CAP) { atomicAdd(&bar[XB_TMO], 1u); break; } }
;     }
;     nloc = mine > 0u ? mine : 1u; nx = cnt > 0u ? cnt : 1u;
; }
.LBB0_3690:
	global_load_dword v15, v16, s[4:5] sc1
	global_load_dword v0, v16, s[6:7] sc1
	global_load_dword v1, v16, s[8:9] sc1
	global_load_dword v2, v16, s[10:11] sc1
	global_load_dword v3, v16, s[12:13] sc1
	global_load_dword v4, v16, s[14:15] sc1
	global_load_dword v5, v16, s[18:19] sc1
	global_load_dword v6, v16, s[20:21] sc1
	global_load_dword v7, v16, s[22:23] sc1
	global_load_dword v8, v16, s[24:25] sc1
	global_load_dword v9, v16, s[30:31] sc1
	global_load_dword v10, v16, s[34:35] sc1
	global_load_dword v11, v16, s[36:37] sc1
	global_load_dword v12, v16, s[38:39] sc1
	global_load_dword v13, v16, s[40:41] sc1
	global_load_dword v14, v16, s[42:43] sc1
	s_mov_b64 s[44:45], -1
	s_mov_b64 s[46:47], -1
	s_waitcnt vmcnt(14)
	v_add_u32_e32 v17, v0, v15
	s_waitcnt vmcnt(13)
	v_add_u32_e32 v17, v17, v1
	s_waitcnt vmcnt(12)
	v_add_u32_e32 v17, v17, v2
	s_waitcnt vmcnt(11)
	v_add_u32_e32 v17, v17, v3
	s_waitcnt vmcnt(10)
	v_add_u32_e32 v17, v17, v4
	s_waitcnt vmcnt(9)
	v_add_u32_e32 v17, v17, v5
	s_waitcnt vmcnt(8)
	v_add_u32_e32 v17, v17, v6
	s_waitcnt vmcnt(7)
	v_add_u32_e32 v17, v17, v7
	s_waitcnt vmcnt(6)
	v_add_u32_e32 v17, v17, v8
	s_waitcnt vmcnt(5)
	v_add_u32_e32 v17, v17, v9
	s_waitcnt vmcnt(4)
	v_add_u32_e32 v17, v17, v10
	s_waitcnt vmcnt(3)
	v_add_u32_e32 v17, v17, v11
	s_waitcnt vmcnt(2)
	v_add_u32_e32 v17, v17, v12
	s_waitcnt vmcnt(1)
	v_add_u32_e32 v17, v17, v13
	s_waitcnt vmcnt(0)
	v_add_u32_e32 v17, v17, v14
	v_cmp_eq_u32_e32 vcc, s50, v17
	s_cbranch_vccnz .LBB0_3689
	s_and_b32 s44, s51, 0xff
	s_cmp_eq_u32 s44, 0
	s_mov_b64 s[44:45], -1
	s_mov_b64 s[48:49], -1
	s_nop 0
	s_cbranch_scc0 .LBB0_3694
	global_load_dword v17, v16, s[2:3] sc1
	s_waitcnt vmcnt(0)
	v_cmp_eq_u32_e32 vcc, 0, v17
	s_cbranch_vccnz .LBB0_3696
	s_mov_b64 s[48:49], 0

; DI unsigned xb_ld(unsigned* p)              { return __hip_atomic_load(p, __ATOMIC_RELAXED, __HIP_MEMORY_SCOPE_AGENT); }
; DI unsigned xb_add(unsigned* p, unsigned v) { return __hip_atomic_fetch_add(p, v, __ATOMIC_RELAXED, __HIP_MEMORY_SCOPE_AGENT); }
; #define XB_SPIN(cond, bar) do { unsigned _sp = 0; while (cond) { __builtin_amdgcn_s_sleep(1); \
;     if ((++_sp & 255u) == 0u) { if (xb_ld(&(bar)[XB_TMO])) break; if (_sp > XB_SPIN_CAP) { atomicAdd(&(bar)[XB_TMO], 1u); break; } } } } while (0)
; DI void xcd_barrier(const XcdBarrier& b) {
;     ...
;             const unsigned og = xb_add(&bar[XB_TOP], 1u);
;             const unsigned tg = og / nx;
;             if (og + 1u == (tg + 1u) * nx) xb_add(&bar[XB_TOPGEN], 1u);
;             else XB_SPIN(xb_ld(&bar[XB_TOPGEN]) == tg, bar);
;             __builtin_amdgcn_fence(__ATOMIC_ACQUIRE, "agent");
;             xb_add(&bar[XB_XGEN(b.x)], 1u);
;             asm volatile("s_waitcnt vmcnt(0)" ::: "memory");
;         } else {
;             XB_SPIN(xb_ld(&bar[XB_XGEN(b.x)]) == gen, bar);
;             __builtin_amdgcn_fence(__ATOMIC_ACQUIRE, "agent");
;             asm volatile("s_waitcnt vmcnt(0)" ::: "memory");
.LBB0_3708:
	s_and_b32 s20, s24, 0xff
	s_mov_b64 s[18:19], -1
	s_cmp_lg_u32 s20, 0
	s_mov_b64 s[22:23], -1
	s_nop 0
	s_cbranch_scc1 .LBB0_3711
	global_load_dword v2, v0, s[8:9] sc1
	s_waitcnt vmcnt(0)
	v_cmp_eq_u32_e32 vcc, 0, v2
	s_cbranch_vccnz .LBB0_3713
	s_mov_b64 s[22:23], 0
	s_mov_b64 s[20:21], -1

; DI unsigned xb_ld(unsigned* p)              { return __hip_atomic_load(p, __ATOMIC_RELAXED, __HIP_MEMORY_SCOPE_AGENT); }
; DI unsigned xb_add(unsigned* p, unsigned v) { return __hip_atomic_fetch_add(p, v, __ATOMIC_RELAXED, __HIP_MEMORY_SCOPE_AGENT); }
; #define XB_SPIN(cond, bar) do { unsigned _sp = 0; while (cond) { __builtin_amdgcn_s_sleep(1); \
;     if ((++_sp & 255u) == 0u) { if (xb_ld(&(bar)[XB_TMO])) break; if (_sp > XB_SPIN_CAP) { atomicAdd(&(bar)[XB_TMO], 1u); break; } } } } while (0)
; DI void xcd_barrier(const XcdBarrier& b) {
;     ...
;             const unsigned og = xb_add(&bar[XB_TOP], 1u);
;             const unsigned tg = og / nx;
;             if (og + 1u == (tg + 1u) * nx) xb_add(&bar[XB_TOPGEN], 1u);
;             else XB_SPIN(xb_ld(&bar[XB_TOPGEN]) == tg, bar);
;             __builtin_amdgcn_fence(__ATOMIC_ACQUIRE, "agent");
;             xb_add(&bar[XB_XGEN(b.x)], 1u);
;             asm volatile("s_waitcnt vmcnt(0)" ::: "memory");
;         } else {
;             XB_SPIN(xb_ld(&bar[XB_XGEN(b.x)]) == gen, bar);
;             __builtin_amdgcn_fence(__ATOMIC_ACQUIRE, "agent");
;             asm volatile("s_waitcnt vmcnt(0)" ::: "memory");
.LBB0_3725:
	s_and_b32 s18, s24, 0xff
	s_cmp_lg_u32 s18, 0
	s_mov_b64 s[20:21], -1
	s_nop 0
	s_cbranch_scc1 .LBB0_3728
	global_load_dword v1, v0, s[8:9] sc1
	s_waitcnt vmcnt(0)
	v_cmp_eq_u32_e32 vcc, 0, v1
	s_cbranch_vccnz .LBB0_3730
	s_mov_b64 s[20:21], 0
	s_mov_b64 s[18:19], -1
